# attention: exact-zero subtile skip (all scores > 160 log2 units under the running max: exps of half 1 and PV skipped, bit-identical) + static table dealing (head, q-block) items to workgroups so skipp
# speedup vs baseline: 1.0091x; 1.0091x over previous
.LBB0_732:
	s_cmp_lt_i32 s62, 7
	s_cselect_b64 s[4:5], -1, 0
	s_and_b64 s[2:3], s[4:5], s[2:3]
	s_andn2_b64 vcc, exec, s[2:3]
	s_cbranch_vccnz .LBB0_810
	v_lshlrev_b32_e32 v0, 2, v206
	global_load_dword v1, v0, s[50:51]
	global_load_dword v2, v0, s[50:51] offset:256
	global_load_dword v3, v0, s[50:51] offset:512
	global_load_dword v4, v0, s[50:51] offset:768
	v_mbcnt_lo_u32_b32 v0, -1, 0
	v_mbcnt_hi_u32_b32 v0, -1, v0
	v_and_b32_e32 v5, 64, v0
	v_xor_b32_e32 v6, 1, v0
	v_add_u32_e32 v5, 64, v5
	v_cmp_lt_i32_e32 vcc, v6, v5
	v_xor_b32_e32 v7, 2, v0
	v_xor_b32_e32 v8, 4, v0
	v_cndmask_b32_e32 v6, v0, v6, vcc
	v_lshlrev_b32_e32 v6, 2, v6
	v_cmp_lt_i32_e32 vcc, v7, v5
	v_xor_b32_e32 v9, 8, v0
	v_xor_b32_e32 v10, 16, v0
	v_cndmask_b32_e32 v7, v0, v7, vcc
	v_lshlrev_b32_e32 v7, 2, v7
	v_cmp_lt_i32_e32 vcc, v8, v5
	v_xor_b32_e32 v11, 32, v0
	s_cmpk_gt_i32 s33, 0xff
	s_mov_b32 s47, 0
	s_waitcnt vmcnt(0)
	v_mul_f32_e32 v12, v1, v2
	ds_bpermute_b32 v12, v6, v12
	v_mul_f32_e32 v13, v3, v4
	ds_bpermute_b32 v6, v6, v13
	s_waitcnt lgkmcnt(1)
	v_fmac_f32_e32 v12, v1, v2
	ds_bpermute_b32 v1, v7, v12
	s_waitcnt lgkmcnt(1)
	v_fmac_f32_e32 v6, v3, v4
	ds_bpermute_b32 v2, v7, v6
	v_cndmask_b32_e32 v3, v0, v8, vcc
	v_lshlrev_b32_e32 v3, 2, v3
	s_waitcnt lgkmcnt(1)
	v_add_f32_e32 v1, v12, v1
	ds_bpermute_b32 v4, v3, v1
	s_waitcnt lgkmcnt(1)
	v_add_f32_e32 v2, v6, v2
	ds_bpermute_b32 v3, v3, v2
	v_cmp_lt_i32_e32 vcc, v9, v5
	s_waitcnt lgkmcnt(1)
	v_add_f32_e32 v1, v1, v4
	v_cndmask_b32_e32 v6, v0, v9, vcc
	v_lshlrev_b32_e32 v6, 2, v6
	s_waitcnt lgkmcnt(0)
	v_add_f32_e32 v2, v2, v3
	ds_bpermute_b32 v3, v6, v1
	ds_bpermute_b32 v4, v6, v2
	v_cmp_lt_i32_e32 vcc, v10, v5
	s_waitcnt lgkmcnt(1)
	v_add_f32_e32 v1, v1, v3
	v_cndmask_b32_e32 v6, v0, v10, vcc
	v_lshlrev_b32_e32 v6, 2, v6
	s_waitcnt lgkmcnt(0)
	v_add_f32_e32 v3, v2, v4
	ds_bpermute_b32 v2, v6, v1
	ds_bpermute_b32 v4, v6, v3
	v_cmp_lt_i32_e32 vcc, v11, v5
	s_waitcnt lgkmcnt(1)
	v_add_f32_e32 v2, v1, v2
	v_cndmask_b32_e32 v0, v0, v11, vcc
	v_lshlrev_b32_e32 v5, 2, v0
	s_waitcnt lgkmcnt(0)
	v_add_f32_e32 v0, v3, v4
	ds_bpermute_b32 v3, v5, v2
	ds_bpermute_b32 v1, v5, v0
	s_cbranch_scc1 .LBB0_810
	v_writelane_b32 v243, s2, 7
	s_waitcnt lgkmcnt(1)
	v_add_f32_e32 v2, v2, v3
	v_mul_f32_e32 v3, 0x3fb8aa3b, v2
	v_writelane_b32 v243, s3, 8
	s_mov_b32 s2, 0x3fb8aa3b
	v_fma_f32 v4, v2, s2, -v3
	v_rndne_f32_e32 v5, v3
	v_fmac_f32_e32 v4, 0x32a5705f, v2
	v_sub_f32_e32 v3, v3, v5
	v_add_f32_e32 v3, v3, v4
	v_exp_f32_e32 v3, v3
	v_cvt_i32_f32_e32 v4, v5
	s_waitcnt lgkmcnt(0)
	v_add_f32_e32 v0, v0, v1
	s_mov_b32 s3, 0xc2ce8ed0
	v_cmp_ngt_f32_e32 vcc, s3, v2
	v_ldexp_f32 v1, v3, v4
	v_mul_f32_e32 v3, 0x3fb8aa3b, v0
	v_fma_f32 v4, v0, s2, -v3
	v_rndne_f32_e32 v5, v3
	v_fmac_f32_e32 v4, 0x32a5705f, v0
	v_sub_f32_e32 v3, v3, v5
	v_add_f32_e32 v3, v3, v4
	v_exp_f32_e32 v3, v3
	v_cvt_i32_f32_e32 v4, v5
	s_mov_b32 s4, 0x42b17218
	v_cndmask_b32_e32 v1, 0, v1, vcc
	v_mov_b32_e32 v5, 0x7f800000
	v_cmp_nlt_f32_e32 vcc, s4, v2
	v_ldexp_f32 v2, v3, v4
	v_lshrrev_b32_e32 v3, 1, v207
	v_cndmask_b32_e32 v1, v5, v1, vcc
	v_cmp_ngt_f32_e32 vcc, s3, v0
	v_and_b32_e32 v3, 4, v3
	v_lshrrev_b32_e32 v210, 5, v206
	v_cndmask_b32_e32 v2, 0, v2, vcc
	v_cmp_nlt_f32_e32 vcc, s4, v0
	v_lshlrev_b32_e32 v176, 4, v210
	v_mov_b32_e32 v177, 0
	v_cndmask_b32_e32 v0, v5, v2, vcc
	v_lshlrev_b32_e32 v2, 1, v207
	v_sub_f32_e32 v0, v1, v0
	v_and_b32_e32 v1, 19, v207
	v_and_b32_e32 v2, 8, v2
	v_or3_b32 v1, v2, v1, v3
	v_lshlrev_b32_e32 v2, 8, v1
	v_bitop3_b32 v1, v1, v210, 15 bitop3:0x6c
	v_lshl_add_u64 v[178:179], s[0:1], 0, v[176:177]
	v_lshlrev_b32_e32 v1, 4, v1
	s_movk_i32 s0, 0x60
	v_bitop3_b32 v6, v1, s0, v2 bitop3:0x36
	s_movk_i32 s0, 0x80
	v_bitop3_b32 v7, v1, s0, v2 bitop3:0x36
	s_movk_i32 s0, 0xa0
	v_bitop3_b32 v8, v1, s0, v2 bitop3:0x36
	s_movk_i32 s0, 0xc0
	v_bitop3_b32 v9, v1, s0, v2 bitop3:0x36
	s_movk_i32 s0, 0xe0
	v_add_f32_e32 v208, 0x3ef1014c, v0
	v_lshlrev_b32_e32 v0, 3, v210
	v_or_b32_e32 v3, v1, v2
	v_bitop3_b32 v4, v1, 32, v2 bitop3:0x36
	v_bitop3_b32 v5, v1, 64, v2 bitop3:0x36
	v_bitop3_b32 v1, v1, s0, v2 bitop3:0x36
	v_bfe_u32 v2, v207, 2, 2
	v_lshrrev_b32_e32 v13, 3, v207
	v_bfe_u32 v14, v207, 1, 1
	v_or_b32_e32 v10, v0, v2
	v_lshlrev_b32_e32 v2, 2, v2
	v_lshlrev_b32_e32 v11, 1, v210
	v_and_or_b32 v13, v13, 2, v14
	v_lshlrev_b32_e32 v14, 3, v207
	v_bitop3_b32 v15, v11, v13, v2 bitop3:0x36
	v_or_b32_e32 v12, v11, v2
	v_and_b32_e32 v14, 8, v14
	v_lshl_add_u32 v10, v10, 8, 0
	v_lshlrev_b32_e32 v15, 4, v15
	v_add3_u32 v215, v10, v15, v14
	v_bitop3_b32 v15, v12, v13, 1 bitop3:0x36
	v_lshlrev_b32_e32 v15, 4, v15
	v_add3_u32 v217, v10, v15, v14
	v_or_b32_e32 v15, 4, v13
	v_bitop3_b32 v16, v11, v15, v2 bitop3:0x36
	v_bitop3_b32 v15, v12, v15, 1 bitop3:0x36
	v_lshlrev_b32_e32 v15, 4, v15
	v_lshlrev_b32_e32 v16, 4, v16
	v_add3_u32 v221, v10, v15, v14
	v_or_b32_e32 v15, 8, v13
	v_or_b32_e32 v13, 12, v13
	v_add3_u32 v219, v10, v16, v14
	v_bitop3_b32 v16, v11, v15, v2 bitop3:0x36
	v_bitop3_b32 v2, v11, v13, v2 bitop3:0x36
	v_lshlrev_b32_e32 v2, 4, v2
	v_add3_u32 v227, v10, v2, v14
	v_bitop3_b32 v2, v12, v13, 1 bitop3:0x36
	v_lshlrev_b32_e32 v2, 4, v2
	v_and_b32_e32 v209, 31, v207
	v_add3_u32 v229, v10, v2, v14
	v_or_b32_e32 v2, 2, v0
	v_cmp_gt_u32_e64 s[6:7], v2, v209
	v_or_b32_e32 v2, 3, v0
	v_cmp_gt_u32_e64 s[8:9], v2, v209
	v_or_b32_e32 v2, 4, v0
	v_cmp_gt_u32_e64 s[10:11], v2, v209
	v_or_b32_e32 v2, 5, v0
	v_cmp_gt_u32_e64 s[12:13], v2, v209
	v_or_b32_e32 v2, 6, v0
	v_cmp_gt_u32_e64 s[14:15], v2, v209
	v_or_b32_e32 v2, 7, v0
	v_cmp_gt_u32_e64 s[16:17], v2, v209
	v_or_b32_e32 v2, 16, v0
	v_cmp_gt_u32_e64 s[18:19], v2, v209
	v_or_b32_e32 v2, 17, v0
	v_cmp_gt_u32_e64 s[20:21], v2, v209
	v_or_b32_e32 v2, 18, v0
	s_add_i32 s2, 0, 0x18000
	v_cmp_gt_u32_e64 s[22:23], v2, v209
	v_or_b32_e32 v2, 19, v0
	v_bitop3_b32 v15, v12, v15, 1 bitop3:0x36
	v_cmp_gt_u32_e64 s[24:25], v2, v209
	v_or_b32_e32 v2, 20, v0
	s_add_u32 s48, s60, 0xe000000
	v_lshlrev_b32_e32 v16, 4, v16
	v_lshlrev_b32_e32 v15, 4, v15
	v_cmp_gt_u32_e64 s[26:27], v2, v209
	v_or_b32_e32 v2, 21, v0
	s_addc_u32 s49, s61, 0
	v_lshl_add_u32 v211, v206, 4, s2
	v_lshrrev_b32_e32 v212, 4, v206
	v_add3_u32 v223, v10, v16, v14
	v_add3_u32 v225, v10, v15, v14
	v_cmp_gt_u32_e64 s[2:3], v0, v209
	v_cmp_lt_u32_e64 s[4:5], v0, v209
	v_cmp_gt_u32_e64 s[28:29], v2, v209
	v_or_b32_e32 v2, 22, v0
	v_or_b32_e32 v0, 23, v0
	s_add_u32 s54, s60, 0x12000000
	v_and_b32_e32 v213, 15, v207
	v_lshlrev_b32_e32 v214, 2, v212
	v_add_u32_e32 v216, 0xc000, v215
	v_add_u32_e32 v218, 0xc400, v217
	v_add_u32_e32 v220, 0xc000, v219
	v_add_u32_e32 v222, 0xc400, v221
	v_add_u32_e32 v224, 0xc000, v223
	v_add_u32_e32 v226, 0xc400, v225
	v_add_u32_e32 v228, 0xc000, v227
	v_add_u32_e32 v230, 0xc400, v229
	v_cmp_gt_u32_e64 s[30:31], v2, v209
	v_cmp_gt_u32_e64 s[34:35], v0, v209
	s_addc_u32 s55, s61, 0
	v_sub_u32_e32 v231, 0, v209
	s_movk_i32 s70, 0xf0
	s_add_i32 s71, 0, 0x10000
	s_add_i32 s72, 0, 0x14000
	v_mov_b32_e32 v232, 0x358637bd
	v_mov_b32_e32 v233, 0x42800000
	v_add_u32_e32 v234, 0, v8
	v_add_u32_e32 v235, 0, v7
	v_add_u32_e32 v236, 0, v4
	v_add_u32_e32 v237, 0, v3
	v_add_u32_e32 v238, 0, v1
	v_add_u32_e32 v239, 0, v9
	v_add_u32_e32 v240, 0, v6
	v_add_u32_e32 v241, 0, v5
	v_mov_b32_e32 v242, 0xff800000
	v_mov_b32_e32 v181, 0x41000000
	s_and_b32 s73, s33, 7
	s_lshl_b32 s73, s73, 5
	s_lshr_b32 s99, s33, 3
	s_add_i32 s73, s73, s99
	s_cmp_lg_u32 s101, 0
	s_cselect_b32 s73, s73, s33
	s_branch .Ltbl

.Ltbl:
	s_and_b32 s0, s73, 15
	s_mov_b32 s100, 0x1a0c7c
	s_cmp_eq_u32 s0, 1
	s_cselect_b32 s100, 0x918bb, s100
	s_cmp_eq_u32 s0, 2
	s_cselect_b32 s100, 0x3d8c3d, s100
	s_cmp_eq_u32 s0, 3
	s_cselect_b32 s100, 0x2d07ff, s100
	s_cmp_eq_u32 s0, 4
	s_cselect_b32 s100, 0x1166fe, s100
	s_cmp_eq_u32 s0, 5
	s_cselect_b32 s100, 0x1d7973, s100
	s_cmp_eq_u32 s0, 6
	s_cselect_b32 s100, 0x14ab4, s100
	s_cmp_eq_u32 s0, 7
	s_cselect_b32 s100, 0x228775, s100
	s_cmp_eq_u32 s0, 8
	s_cselect_b32 s100, 0x313736, s100
	s_cmp_eq_u32 s0, 9
	s_cselect_b32 s100, 0x252e37, s100
	s_cmp_eq_u32 s0, 10
	s_cselect_b32 s100, 0xe98eb, s100
	s_cmp_eq_u32 s0, 11
	s_cselect_b32 s100, 0x5a92c, s100
	s_cmp_eq_u32 s0, 12
	s_cselect_b32 s100, 0x3a1e6d, s100
	s_cmp_eq_u32 s0, 13
	s_cselect_b32 s100, 0x3559ae, s100
	s_cmp_eq_u32 s0, 14
	s_cselect_b32 s100, 0x2999ef, s100
	s_cmp_eq_u32 s0, 15
	s_cselect_b32 s100, 0x15ecba, s100
	s_mov_b32 s74, 0
.LBB0_736:
	s_mul_i32 s0, s74, 6
	s_lshr_b32 s0, s100, s0
	s_and_b32 s36, s0, 7
	s_bfe_u32 s50, s0, 0x30003
	s_add_i32 s0, s36, 1
	v_cvt_f32_ubyte0_e32 v0, s0
	s_mov_b32 s0, 0x42fc0000
	v_cmp_lt_f32_e32 vcc, s0, v0
	s_and_b64 s[0:1], vcc, exec
	s_cselect_b32 s0, 0xffffffc0, 0
	v_cndmask_b32_e32 v1, 0, v233, vcc
	v_sub_f32_e32 v0, v1, v0
	v_exp_f32_e32 v0, v0
	s_lshl_b32 s75, s36, 7
	s_lshl_b32 s46, s36, 8
	v_lshl_add_u64 v[182:183], v[178:179], 0, s[46:47]
	v_ldexp_f32 v0, v0, s0
	s_lshl_b32 s0, s73, 7
	s_and_b32 s0, s0, 0x7800
	s_add_u32 s1, s42, s46
	s_addc_u32 s36, s43, 0
	s_add_u32 s37, s54, s46
	s_addc_u32 s38, s55, 0
	s_mov_b32 s46, s0
	s_lshl_b32 s0, s0, 11
	s_add_u32 s76, s1, s0
	s_addc_u32 s77, s36, 0
	v_mul_f32_e32 v184, 0x3fb8aa3b, v0
	s_add_u32 s81, s37, s0
	s_addc_u32 s82, s38, 0
	v_mov_b32_e32 v186, v184
	v_mov_b32_e32 v187, v184
	s_branch .LBB0_738

.Lpf_do:
	s_mul_i32 s0, s74, 6
	s_lshr_b32 s0, s100, s0
	s_and_b32 s1, s0, 7
	s_bfe_u32 s36, s0, 0x30003
	s_lshl_b32 s1, s1, 8
	s_lshr_b32 s0, s87, 6
	s_lshl_b32 s37, s36, 8
	s_add_i32 s0, s0, s37
	v_or_b32_e32 v148, s0, v209
	v_add_u32_e32 v148, s46, v148
	v_lshlrev_b32_e32 v148, 11, v148
	v_add_u32_e32 v148, s1, v148
	v_add_co_u32_e32 v132, vcc, v178, v148
	s_lshl_b32 s0, s87, 2
	v_addc_co_u32_e32 v133, vcc, 0, v179, vcc
	s_add_i32 s0, s0, 0x18000
	s_mov_b32 m0, s0
	s_nop 0
	global_load_lds_dwordx4 v[132:133], off
	s_add_i32 m0, s0, 992
	s_nop 0
	global_load_lds_dwordx4 v[132:133], off offset:32
	s_add_i32 m0, s0, 1984
	s_nop 0
	global_load_lds_dwordx4 v[132:133], off offset:64
	s_add_i32 m0, s0, 2976
	s_nop 0
	global_load_lds_dwordx4 v[132:133], off offset:96
	s_add_i32 m0, s0, 3968
	s_nop 0
	global_load_lds_dwordx4 v[132:133], off offset:128
	s_add_i32 m0, s0, 4960
	s_nop 0
	global_load_lds_dwordx4 v[132:133], off offset:160
	s_add_i32 m0, s0, 5952
	s_nop 0
	global_load_lds_dwordx4 v[132:133], off offset:192
	s_add_i32 m0, s0, 6944
	s_nop 0
	global_load_lds_dwordx4 v[132:133], off offset:224
	s_lshl_b32 s0, s46, 11
	s_add_i32 s1, s1, s0
	s_lshl_b32 s0, s36, 2
	s_or_b32 s0, s0, 3
	s_lshl_b32 s0, s0, 17
	s_add_i32 s0, s0, s1
	s_add_u32 s40, s42, s0
	s_addc_u32 s41, s43, 0
	s_add_u32 s66, s54, s0
	s_addc_u32 s67, s55, 0
	s_lshl_b32 s0, s36, 19
	s_or_b32 s0, s0, 0x40000
	s_add_i32 s36, s0, s1
	s_add_u32 s0, s42, s36
	s_addc_u32 s1, s43, 0
	s_add_u32 s36, s54, s36
	s_addc_u32 s37, s55, 0
	s_mov_b32 m0, s88
	s_nop 0
	global_load_lds_dwordx4 v176, s[40:41] nt
	s_mov_b32 m0, s89
	s_nop 0
	global_load_lds_dwordx4 v190, s[66:67] nt
	s_mov_b32 m0, s91
	s_nop 0
	global_load_lds_dwordx4 v192, s[40:41] nt
	s_mov_b32 m0, s92
	s_nop 0
	global_load_lds_dwordx4 v194, s[66:67] nt
	s_mov_b32 m0, s93
	s_nop 0
	global_load_lds_dwordx4 v176, s[0:1] nt
	s_mov_b32 m0, s94
	s_nop 0
	global_load_lds_dwordx4 v190, s[36:37] nt
	s_mov_b32 m0, s95
	s_nop 0
	global_load_lds_dwordx4 v192, s[0:1] nt
	s_mov_b32 m0, s96
	s_nop 0
	global_load_lds_dwordx4 v194, s[36:37] nt
.Lpf_done:
	v_mov_b32_e32 v128, v197
	v_mov_b32_e32 v129, v196
	s_nop 0
	v_permlane32_swap_b32_e32 v197, v128
	v_permlane32_swap_b32_e32 v196, v129
	v_add_f32_e32 v148, v197, v128
	v_add_f32_e32 v149, v196, v129
	v_div_scale_f32 v150, s[0:1], v148, v148, 1.0
	v_div_scale_f32 v152, s[0:1], v149, v149, -v208
	v_rcp_f32_e32 v154, v150
	v_rcp_f32_e32 v155, v152
	v_div_scale_f32 v151, vcc, 1.0, v148, 1.0
	v_fma_f32 v156, -v150, v154, 1.0
	v_fma_f32 v157, -v152, v155, 1.0
	v_fmac_f32_e32 v154, v156, v154
	v_div_scale_f32 v153, s[36:37], -v208, v149, -v208
	v_fmac_f32_e32 v155, v157, v155
	v_mul_f32_e32 v156, v151, v154
	v_mul_f32_e32 v157, v153, v155
	v_fma_f32 v158, -v150, v156, v151
	v_fma_f32 v159, -v152, v157, v153
	v_fmac_f32_e32 v156, v158, v154
	v_fmac_f32_e32 v157, v159, v155
	v_fma_f32 v150, -v150, v156, v151
	v_fma_f32 v151, -v152, v157, v153
	v_div_fmas_f32 v150, v150, v154, v156
	s_mov_b64 vcc, s[36:37]
	v_div_fixup_f32 v148, v150, v148, 1.0
	v_div_fmas_f32 v150, v151, v155, v157
	v_div_fixup_f32 v150, v150, v149, -v208
	v_pk_mul_f32 v[96:97], v[96:97], v[150:151] op_sel_hi:[1,0]
	v_pk_mul_f32 v[98:99], v[98:99], v[150:151] op_sel_hi:[1,0]
	v_pk_fma_f32 v[112:113], v[112:113], v[148:149], v[96:97] op_sel_hi:[1,0,1]
	v_pk_fma_f32 v[114:115], v[114:115], v[148:149], v[98:99] op_sel_hi:[1,0,1]
	v_mul_f32_e32 v96, v113, v113
	v_pk_fma_f32 v[96:97], v[112:113], v[112:113], v[96:97] op_sel_hi:[1,1,0]
	v_pk_mul_f32 v[100:101], v[100:101], v[150:151] op_sel_hi:[1,0]
	v_mul_f32_e32 v98, v115, v115
	v_pk_fma_f32 v[96:97], v[114:115], v[114:115], v[96:97]
	v_pk_fma_f32 v[100:101], v[116:117], v[148:149], v[100:101] op_sel_hi:[1,0,1]
	v_pk_add_f32 v[96:97], v[98:99], v[96:97] op_sel_hi:[0,1]
	v_pk_mul_f32 v[102:103], v[102:103], v[150:151] op_sel_hi:[1,0]
	v_mul_f32_e32 v116, v101, v101
	v_pk_fma_f32 v[96:97], v[100:101], v[100:101], v[96:97]
	v_pk_fma_f32 v[102:103], v[118:119], v[148:149], v[102:103] op_sel_hi:[1,0,1]
	v_pk_add_f32 v[96:97], v[116:117], v[96:97] op_sel_hi:[0,1]
	v_pk_mul_f32 v[104:105], v[104:105], v[150:151] op_sel_hi:[1,0]
	v_mul_f32_e32 v118, v103, v103
	v_pk_fma_f32 v[96:97], v[102:103], v[102:103], v[96:97]
	v_pk_fma_f32 v[104:105], v[120:121], v[148:149], v[104:105] op_sel_hi:[1,0,1]
	v_pk_add_f32 v[96:97], v[118:119], v[96:97] op_sel_hi:[0,1]
	v_pk_mul_f32 v[106:107], v[106:107], v[150:151] op_sel_hi:[1,0]
	v_mul_f32_e32 v120, v105, v105
	v_pk_fma_f32 v[96:97], v[104:105], v[104:105], v[96:97]
	v_pk_fma_f32 v[106:107], v[122:123], v[148:149], v[106:107] op_sel_hi:[1,0,1]
	v_pk_add_f32 v[96:97], v[120:121], v[96:97] op_sel_hi:[0,1]
	v_pk_mul_f32 v[108:109], v[108:109], v[150:151] op_sel_hi:[1,0]
	v_mul_f32_e32 v122, v107, v107
	v_pk_fma_f32 v[96:97], v[106:107], v[106:107], v[96:97]
	v_pk_fma_f32 v[108:109], v[124:125], v[148:149], v[108:109] op_sel_hi:[1,0,1]
	v_pk_add_f32 v[96:97], v[122:123], v[96:97] op_sel_hi:[0,1]
	v_pk_mul_f32 v[110:111], v[110:111], v[150:151] op_sel_hi:[1,0]
	v_pk_fma_f32 v[96:97], v[108:109], v[108:109], v[96:97]
	v_mul_f32_e32 v98, v109, v109
	v_pk_fma_f32 v[110:111], v[126:127], v[148:149], v[110:111] op_sel_hi:[1,0,1]
	v_pk_add_f32 v[96:97], v[98:99], v[96:97] op_sel_hi:[0,1]
	v_pk_fma_f32 v[96:97], v[110:111], v[110:111], v[96:97]
	v_mul_f32_e32 v98, v111, v111
	v_pk_mul_f32 v[82:83], v[82:83], v[150:151] op_sel_hi:[1,0]
	v_pk_add_f32 v[118:119], v[98:99], v[96:97] op_sel_hi:[0,1]
	v_pk_fma_f32 v[96:97], v[66:67], v[148:149], v[82:83] op_sel_hi:[1,0,1]
	v_pk_mul_f32 v[66:67], v[80:81], v[150:151] op_sel_hi:[1,0]
	v_lshl_add_u64 v[132:133], v[130:131], 2, s[52:53]
	v_pk_fma_f32 v[98:99], v[64:65], v[148:149], v[66:67] op_sel_hi:[1,0,1]
	v_pk_fma_f32 v[64:65], v[98:99], v[98:99], v[118:119]
	v_mul_f32_e32 v66, v99, v99
	ds_read_b128 v[128:131], v219
	v_pk_add_f32 v[64:65], v[66:67], v[64:65] op_sel_hi:[0,1]
	v_pk_fma_f32 v[64:65], v[96:97], v[96:97], v[64:65]
	v_mul_f32_e32 v66, v97, v97
	v_pk_add_f32 v[64:65], v[66:67], v[64:65] op_sel_hi:[0,1]
	v_pk_mul_f32 v[66:67], v[86:87], v[150:151] op_sel_hi:[1,0]
	v_pk_mul_f32 v[50:51], v[50:51], v[150:151] op_sel_hi:[1,0]
	v_pk_fma_f32 v[80:81], v[70:71], v[148:149], v[66:67] op_sel_hi:[1,0,1]
	v_pk_mul_f32 v[66:67], v[84:85], v[150:151] op_sel_hi:[1,0]
	v_pk_mul_f32 v[18:19], v[18:19], v[150:151] op_sel_hi:[1,0]
	v_pk_fma_f32 v[82:83], v[68:69], v[148:149], v[66:67] op_sel_hi:[1,0,1]
	s_mov_b32 s0, 0x800000
	v_pk_fma_f32 v[64:65], v[82:83], v[82:83], v[64:65]
	v_mul_f32_e32 v66, v83, v83
	v_pk_add_f32 v[64:65], v[66:67], v[64:65] op_sel_hi:[0,1]
	v_pk_fma_f32 v[64:65], v[80:81], v[80:81], v[64:65]
	v_mul_f32_e32 v66, v81, v81
	v_pk_add_f32 v[64:65], v[66:67], v[64:65] op_sel_hi:[0,1]
	v_pk_mul_f32 v[66:67], v[90:91], v[150:151] op_sel_hi:[1,0]
	v_lshl_add_u64 v[140:141], s[68:69], 0, v[140:141]
	v_pk_fma_f32 v[74:75], v[74:75], v[148:149], v[66:67] op_sel_hi:[1,0,1]
	v_pk_mul_f32 v[66:67], v[88:89], v[150:151] op_sel_hi:[1,0]
	v_pk_fma_f32 v[72:73], v[72:73], v[148:149], v[66:67] op_sel_hi:[1,0,1]
	s_cmp_eq_u32 s74, 4
	v_pk_fma_f32 v[64:65], v[72:73], v[72:73], v[64:65]
	v_mul_f32_e32 v66, v73, v73
	v_pk_add_f32 v[64:65], v[66:67], v[64:65] op_sel_hi:[0,1]
	v_pk_fma_f32 v[64:65], v[74:75], v[74:75], v[64:65]
	v_mul_f32_e32 v66, v75, v75
	v_pk_add_f32 v[64:65], v[66:67], v[64:65] op_sel_hi:[0,1]
	v_pk_mul_f32 v[66:67], v[94:95], v[150:151] op_sel_hi:[1,0]
	s_waitcnt vmcnt(16) lgkmcnt(0)
	v_lshlrev_b32_e32 v116, 16, v160
	v_pk_fma_f32 v[68:69], v[78:79], v[148:149], v[66:67] op_sel_hi:[1,0,1]
	v_pk_mul_f32 v[66:67], v[92:93], v[150:151] op_sel_hi:[1,0]
	v_and_b32_e32 v117, 0xffff0000, v160
	v_pk_fma_f32 v[70:71], v[76:77], v[148:149], v[66:67] op_sel_hi:[1,0,1]
	s_nop 0
	v_pk_fma_f32 v[64:65], v[70:71], v[70:71], v[64:65]
	v_mul_f32_e32 v66, v71, v71
	v_pk_add_f32 v[64:65], v[66:67], v[64:65] op_sel_hi:[0,1]
	v_pk_fma_f32 v[64:65], v[68:69], v[68:69], v[64:65]
	v_mul_f32_e32 v66, v69, v69
	v_pk_add_f32 v[76:77], v[66:67], v[64:65] op_sel_hi:[0,1]
	v_pk_fma_f32 v[64:65], v[34:35], v[148:149], v[50:51] op_sel_hi:[1,0,1]
	v_pk_mul_f32 v[34:35], v[48:49], v[150:151] op_sel_hi:[1,0]
	s_nop 0
	v_pk_fma_f32 v[66:67], v[32:33], v[148:149], v[34:35] op_sel_hi:[1,0,1]
	s_nop 0
	v_pk_fma_f32 v[32:33], v[66:67], v[66:67], v[76:77]
	v_mul_f32_e32 v34, v67, v67
	v_pk_add_f32 v[32:33], v[34:35], v[32:33] op_sel_hi:[0,1]
	v_pk_fma_f32 v[32:33], v[64:65], v[64:65], v[32:33]
	v_mul_f32_e32 v34, v65, v65
	v_pk_add_f32 v[32:33], v[34:35], v[32:33] op_sel_hi:[0,1]
	v_pk_mul_f32 v[34:35], v[54:55], v[150:151] op_sel_hi:[1,0]
	s_nop 0
	v_pk_fma_f32 v[48:49], v[38:39], v[148:149], v[34:35] op_sel_hi:[1,0,1]
	v_pk_mul_f32 v[34:35], v[52:53], v[150:151] op_sel_hi:[1,0]
	s_nop 0
	v_pk_fma_f32 v[50:51], v[36:37], v[148:149], v[34:35] op_sel_hi:[1,0,1]
	s_nop 0
	v_pk_fma_f32 v[32:33], v[50:51], v[50:51], v[32:33]
	v_mul_f32_e32 v34, v51, v51
	v_pk_add_f32 v[32:33], v[34:35], v[32:33] op_sel_hi:[0,1]
	v_pk_fma_f32 v[32:33], v[48:49], v[48:49], v[32:33]
	v_mul_f32_e32 v34, v49, v49
	v_pk_add_f32 v[32:33], v[34:35], v[32:33] op_sel_hi:[0,1]
	v_pk_mul_f32 v[34:35], v[58:59], v[150:151] op_sel_hi:[1,0]
	s_nop 0
	v_pk_fma_f32 v[42:43], v[42:43], v[148:149], v[34:35] op_sel_hi:[1,0,1]
	v_pk_mul_f32 v[34:35], v[56:57], v[150:151] op_sel_hi:[1,0]
	s_nop 0
	v_pk_fma_f32 v[40:41], v[40:41], v[148:149], v[34:35] op_sel_hi:[1,0,1]
	s_nop 0
	v_pk_fma_f32 v[32:33], v[40:41], v[40:41], v[32:33]
	v_mul_f32_e32 v34, v41, v41
	v_pk_add_f32 v[32:33], v[34:35], v[32:33] op_sel_hi:[0,1]
	v_pk_fma_f32 v[32:33], v[42:43], v[42:43], v[32:33]
	v_mul_f32_e32 v34, v43, v43
	v_pk_add_f32 v[32:33], v[34:35], v[32:33] op_sel_hi:[0,1]
	v_pk_mul_f32 v[34:35], v[62:63], v[150:151] op_sel_hi:[1,0]
	s_nop 0
	v_pk_fma_f32 v[36:37], v[46:47], v[148:149], v[34:35] op_sel_hi:[1,0,1]
	v_pk_mul_f32 v[34:35], v[60:61], v[150:151] op_sel_hi:[1,0]
	s_nop 0
	v_pk_fma_f32 v[38:39], v[44:45], v[148:149], v[34:35] op_sel_hi:[1,0,1]
	s_nop 0
	v_pk_fma_f32 v[32:33], v[38:39], v[38:39], v[32:33]
	v_mul_f32_e32 v34, v39, v39
	v_pk_add_f32 v[32:33], v[34:35], v[32:33] op_sel_hi:[0,1]
	v_pk_fma_f32 v[32:33], v[36:37], v[36:37], v[32:33]
	v_mul_f32_e32 v34, v37, v37
	v_pk_add_f32 v[44:45], v[34:35], v[32:33] op_sel_hi:[0,1]
	v_pk_fma_f32 v[32:33], v[2:3], v[148:149], v[18:19] op_sel_hi:[1,0,1]
	v_pk_mul_f32 v[2:3], v[16:17], v[150:151] op_sel_hi:[1,0]
	s_nop 0
	v_pk_fma_f32 v[34:35], v[0:1], v[148:149], v[2:3] op_sel_hi:[1,0,1]
	s_nop 0
	v_pk_fma_f32 v[0:1], v[34:35], v[34:35], v[44:45]
	v_mul_f32_e32 v2, v35, v35
	v_pk_add_f32 v[0:1], v[2:3], v[0:1] op_sel_hi:[0,1]
	v_pk_fma_f32 v[0:1], v[32:33], v[32:33], v[0:1]
	v_mul_f32_e32 v2, v33, v33
	v_pk_add_f32 v[0:1], v[2:3], v[0:1] op_sel_hi:[0,1]
	v_pk_mul_f32 v[2:3], v[22:23], v[150:151] op_sel_hi:[1,0]
	v_lshlrev_b32_e32 v22, 16, v165
	v_pk_fma_f32 v[16:17], v[6:7], v[148:149], v[2:3] op_sel_hi:[1,0,1]
	v_pk_mul_f32 v[2:3], v[20:21], v[150:151] op_sel_hi:[1,0]
	v_and_b32_e32 v23, 0xffff0000, v165
	v_pk_fma_f32 v[18:19], v[4:5], v[148:149], v[2:3] op_sel_hi:[1,0,1]
	s_nop 0
	v_pk_fma_f32 v[0:1], v[18:19], v[18:19], v[0:1]
	v_mul_f32_e32 v2, v19, v19
	v_pk_add_f32 v[0:1], v[2:3], v[0:1] op_sel_hi:[0,1]
	v_pk_fma_f32 v[0:1], v[16:17], v[16:17], v[0:1]
	v_mul_f32_e32 v2, v17, v17
	v_pk_add_f32 v[0:1], v[2:3], v[0:1] op_sel_hi:[0,1]
	v_pk_mul_f32 v[2:3], v[26:27], v[150:151] op_sel_hi:[1,0]
	s_nop 0
	v_pk_fma_f32 v[10:11], v[10:11], v[148:149], v[2:3] op_sel_hi:[1,0,1]
	v_pk_mul_f32 v[2:3], v[24:25], v[150:151] op_sel_hi:[1,0]
	s_nop 0
	v_pk_fma_f32 v[8:9], v[8:9], v[148:149], v[2:3] op_sel_hi:[1,0,1]
	s_nop 0
	v_pk_fma_f32 v[0:1], v[8:9], v[8:9], v[0:1]
	v_mul_f32_e32 v2, v9, v9
	v_pk_add_f32 v[0:1], v[2:3], v[0:1] op_sel_hi:[0,1]
	v_pk_fma_f32 v[0:1], v[10:11], v[10:11], v[0:1]
	v_mul_f32_e32 v2, v11, v11
	v_pk_add_f32 v[4:5], v[2:3], v[0:1] op_sel_hi:[0,1]
	v_pk_mul_f32 v[2:3], v[28:29], v[150:151] op_sel_hi:[1,0]
	v_pk_mul_f32 v[0:1], v[30:31], v[150:151] op_sel_hi:[1,0]
	v_pk_fma_f32 v[2:3], v[12:13], v[148:149], v[2:3] op_sel_hi:[1,0,1]
	v_pk_fma_f32 v[0:1], v[14:15], v[148:149], v[0:1] op_sel_hi:[1,0,1]
	v_pk_fma_f32 v[4:5], v[2:3], v[2:3], v[4:5]
	v_mul_f32_e32 v6, v3, v3
	v_pk_add_f32 v[4:5], v[6:7], v[4:5] op_sel_hi:[0,1]
	v_pk_fma_f32 v[4:5], v[0:1], v[0:1], v[4:5]
	v_mul_f32_e32 v6, v1, v1
	v_pk_add_f32 v[4:5], v[6:7], v[4:5] op_sel_hi:[0,1]
	v_mov_b32_e32 v5, v4
	s_nop 1
	v_permlane32_swap_b32_e32 v4, v5
	v_add_f32_e32 v4, v4, v5
	v_fmamk_f32 v4, v4, 0x3c000000, v232
	v_mul_f32_e32 v5, 0x4b800000, v4
	v_cmp_gt_f32_e32 vcc, s0, v4
	v_lshlrev_b32_e32 v12, 16, v161
	v_and_b32_e32 v13, 0xffff0000, v161
	v_cndmask_b32_e32 v4, v4, v5, vcc
	v_rsq_f32_e32 v6, v4
	v_lshl_add_u64 v[4:5], v[140:141], 0, v[136:137]
	v_mul_f32_e32 v7, 0x45800000, v6
	v_cndmask_b32_e32 v6, v6, v7, vcc
	v_mul_f32_e32 v6, 0x3f077f5a, v6
	v_pk_mul_f32 v[14:15], v[112:113], v[6:7] op_sel_hi:[1,0]
	v_pk_mul_f32 v[20:21], v[114:115], v[6:7] op_sel_hi:[1,0]
	v_pk_mul_f32 v[14:15], v[128:129], v[14:15]
	v_pk_mul_f32 v[20:21], v[130:131], v[20:21]
	v_pk_mul_f32 v[14:15], v[14:15], v[116:117]
	v_pk_mul_f32 v[12:13], v[20:21], v[12:13]
	v_cvt_pk_bf16_f32 v14, v14, v15
	v_cvt_pk_bf16_f32 v15, v12, v13
	global_store_dwordx2 v[4:5], v[14:15], off
	ds_read_b128 v[12:15], v219 offset:32
	v_pk_mul_f32 v[20:21], v[100:101], v[6:7] op_sel_hi:[1,0]
	v_pk_mul_f32 v[24:25], v[104:105], v[6:7] op_sel_hi:[1,0]
	v_pk_mul_f32 v[26:27], v[106:107], v[6:7] op_sel_hi:[1,0]
	v_pk_mul_f32 v[28:29], v[110:111], v[6:7] op_sel_hi:[1,0]
	v_pk_mul_f32 v[30:31], v[98:99], v[6:7] op_sel_hi:[1,0]
	v_pk_mul_f32 v[44:45], v[96:97], v[6:7] op_sel_hi:[1,0]
	v_pk_mul_f32 v[32:33], v[32:33], v[6:7] op_sel_hi:[1,0]
	v_pk_mul_f32 v[18:19], v[18:19], v[6:7] op_sel_hi:[1,0]
	v_pk_mul_f32 v[16:17], v[16:17], v[6:7] op_sel_hi:[1,0]
	v_pk_mul_f32 v[8:9], v[8:9], v[6:7] op_sel_hi:[1,0]
	v_pk_mul_f32 v[10:11], v[10:11], v[6:7] op_sel_hi:[1,0]
	v_pk_mul_f32 v[2:3], v[2:3], v[6:7] op_sel_hi:[1,0]
	v_pk_mul_f32 v[0:1], v[0:1], v[6:7] op_sel_hi:[1,0]
	s_waitcnt lgkmcnt(0)
	v_pk_mul_f32 v[12:13], v[12:13], v[20:21]
	v_lshlrev_b32_e32 v20, 16, v162
	v_and_b32_e32 v21, 0xffff0000, v162
	v_pk_mul_f32 v[12:13], v[12:13], v[20:21]
	v_pk_mul_f32 v[20:21], v[102:103], v[6:7] op_sel_hi:[1,0]
	v_cvt_pk_bf16_f32 v12, v12, v13
	v_pk_mul_f32 v[14:15], v[14:15], v[20:21]
	v_lshlrev_b32_e32 v20, 16, v163
	v_and_b32_e32 v21, 0xffff0000, v163
	v_pk_mul_f32 v[14:15], v[14:15], v[20:21]
	v_lshlrev_b32_e32 v20, 16, v164
	v_cvt_pk_bf16_f32 v13, v14, v15
	global_store_dwordx2 v[4:5], v[12:13], off offset:16
	ds_read_b128 v[12:15], v219 offset:64
	v_and_b32_e32 v21, 0xffff0000, v164
	s_waitcnt lgkmcnt(0)
	v_pk_mul_f32 v[12:13], v[12:13], v[24:25]
	v_pk_mul_f32 v[14:15], v[14:15], v[26:27]
	v_pk_mul_f32 v[12:13], v[12:13], v[20:21]
	v_pk_mul_f32 v[14:15], v[14:15], v[22:23]
	v_cvt_pk_bf16_f32 v12, v12, v13
	v_cvt_pk_bf16_f32 v13, v14, v15
	global_store_dwordx2 v[4:5], v[12:13], off offset:32
	ds_read_b128 v[12:15], v219 offset:96
	s_nop 0
	v_pk_mul_f32 v[26:27], v[108:109], v[6:7] op_sel_hi:[1,0]
	v_lshlrev_b32_e32 v22, 16, v166
	v_and_b32_e32 v23, 0xffff0000, v166
	v_lshlrev_b32_e32 v24, 16, v167
	v_and_b32_e32 v25, 0xffff0000, v167
	s_waitcnt lgkmcnt(0)
	v_pk_mul_f32 v[12:13], v[12:13], v[26:27]
	v_pk_mul_f32 v[14:15], v[14:15], v[28:29]
	v_pk_mul_f32 v[12:13], v[12:13], v[22:23]
	v_pk_mul_f32 v[14:15], v[14:15], v[24:25]
	v_cvt_pk_bf16_f32 v12, v12, v13
	v_cvt_pk_bf16_f32 v13, v14, v15
	global_store_dwordx2 v[4:5], v[12:13], off offset:48
	ds_read_b128 v[12:15], v219 offset:128
	s_nop 0
	v_lshlrev_b32_e32 v28, 16, v168
	v_and_b32_e32 v29, 0xffff0000, v168
	v_lshlrev_b32_e32 v20, 16, v169
	v_and_b32_e32 v21, 0xffff0000, v169
	s_waitcnt lgkmcnt(0)
	v_pk_mul_f32 v[12:13], v[30:31], v[12:13]
	v_pk_mul_f32 v[14:15], v[44:45], v[14:15]
	v_pk_mul_f32 v[12:13], v[12:13], v[28:29]
	v_pk_mul_f32 v[14:15], v[14:15], v[20:21]
	v_cvt_pk_bf16_f32 v12, v12, v13
	v_cvt_pk_bf16_f32 v13, v14, v15
	global_store_dwordx2 v[4:5], v[12:13], off offset:64
	ds_read_b128 v[12:15], v219 offset:160
	v_pk_mul_f32 v[28:29], v[82:83], v[6:7] op_sel_hi:[1,0]
	v_pk_mul_f32 v[30:31], v[80:81], v[6:7] op_sel_hi:[1,0]
	v_lshlrev_b32_e32 v20, 16, v170
	v_and_b32_e32 v21, 0xffff0000, v170
	v_lshlrev_b32_e32 v22, 16, v171
	v_and_b32_e32 v23, 0xffff0000, v171
	v_pk_mul_f32 v[44:45], v[64:65], v[6:7] op_sel_hi:[1,0]
	s_waitcnt lgkmcnt(0)
	v_pk_mul_f32 v[12:13], v[28:29], v[12:13]
	v_pk_mul_f32 v[14:15], v[30:31], v[14:15]
	v_pk_mul_f32 v[12:13], v[12:13], v[20:21]
	v_pk_mul_f32 v[14:15], v[14:15], v[22:23]
	v_cvt_pk_bf16_f32 v12, v12, v13
	v_cvt_pk_bf16_f32 v13, v14, v15
	global_store_dwordx2 v[4:5], v[12:13], off offset:80
	ds_read_b128 v[12:15], v219 offset:192
	v_lshlrev_b32_e32 v20, 16, v172
	v_and_b32_e32 v21, 0xffff0000, v172
	v_lshlrev_b32_e32 v22, 16, v173
	v_and_b32_e32 v23, 0xffff0000, v173
	v_pk_mul_f32 v[24:25], v[72:73], v[6:7] op_sel_hi:[1,0]
	v_pk_mul_f32 v[28:29], v[74:75], v[6:7] op_sel_hi:[1,0]
	v_pk_mul_f32 v[30:31], v[66:67], v[6:7] op_sel_hi:[1,0]
	s_waitcnt lgkmcnt(0)
	v_pk_mul_f32 v[12:13], v[24:25], v[12:13]
	v_pk_mul_f32 v[14:15], v[28:29], v[14:15]
	v_pk_mul_f32 v[12:13], v[12:13], v[20:21]
	v_pk_mul_f32 v[14:15], v[14:15], v[22:23]
	v_cvt_pk_bf16_f32 v12, v12, v13
	v_cvt_pk_bf16_f32 v13, v14, v15
	global_store_dwordx2 v[4:5], v[12:13], off offset:96
	ds_read_b128 v[12:15], v219 offset:224
	s_nop 0
	v_lshlrev_b32_e32 v22, 16, v174
	v_and_b32_e32 v23, 0xffff0000, v174
	v_lshlrev_b32_e32 v24, 16, v175
	v_and_b32_e32 v25, 0xffff0000, v175
	v_pk_mul_f32 v[26:27], v[70:71], v[6:7] op_sel_hi:[1,0]
	v_pk_mul_f32 v[28:29], v[68:69], v[6:7] op_sel_hi:[1,0]
	s_waitcnt lgkmcnt(0)
	v_pk_mul_f32 v[12:13], v[26:27], v[12:13]
	v_pk_mul_f32 v[14:15], v[28:29], v[14:15]
	v_pk_mul_f32 v[12:13], v[12:13], v[22:23]
	v_pk_mul_f32 v[14:15], v[14:15], v[24:25]
	v_cvt_pk_bf16_f32 v12, v12, v13
	v_cvt_pk_bf16_f32 v13, v14, v15
	global_store_dwordx2 v[4:5], v[12:13], off offset:112
	ds_read_b128 v[12:15], v219 offset:256
	s_nop 0
	v_lshlrev_b32_e32 v28, 16, v202
	v_and_b32_e32 v29, 0xffff0000, v202
	v_lshlrev_b32_e32 v20, 16, v203
	v_and_b32_e32 v21, 0xffff0000, v203
	s_waitcnt lgkmcnt(0)
	v_pk_mul_f32 v[12:13], v[30:31], v[12:13]
	v_pk_mul_f32 v[14:15], v[44:45], v[14:15]
	v_pk_mul_f32 v[12:13], v[12:13], v[28:29]
	v_pk_mul_f32 v[14:15], v[14:15], v[20:21]
	v_cvt_pk_bf16_f32 v12, v12, v13
	v_cvt_pk_bf16_f32 v13, v14, v15
	global_store_dwordx2 v[4:5], v[12:13], off offset:128
	ds_read_b128 v[12:15], v219 offset:288
	v_pk_mul_f32 v[28:29], v[50:51], v[6:7] op_sel_hi:[1,0]
	v_pk_mul_f32 v[30:31], v[48:49], v[6:7] op_sel_hi:[1,0]
	v_lshlrev_b32_e32 v20, 16, v204
	v_and_b32_e32 v21, 0xffff0000, v204
	v_lshlrev_b32_e32 v22, 16, v205
	v_and_b32_e32 v23, 0xffff0000, v205
	s_waitcnt lgkmcnt(0)
	v_pk_mul_f32 v[12:13], v[28:29], v[12:13]
	v_pk_mul_f32 v[14:15], v[30:31], v[14:15]
	v_pk_mul_f32 v[12:13], v[12:13], v[20:21]
	v_pk_mul_f32 v[14:15], v[14:15], v[22:23]
	v_cvt_pk_bf16_f32 v12, v12, v13
	v_cvt_pk_bf16_f32 v13, v14, v15
	global_store_dwordx2 v[4:5], v[12:13], off offset:144
	ds_read_b128 v[12:15], v219 offset:320
	v_lshlrev_b32_e32 v20, 16, v244
	v_and_b32_e32 v21, 0xffff0000, v244
	v_lshlrev_b32_e32 v22, 16, v245
	v_and_b32_e32 v23, 0xffff0000, v245
	v_pk_mul_f32 v[24:25], v[40:41], v[6:7] op_sel_hi:[1,0]
	v_pk_mul_f32 v[28:29], v[42:43], v[6:7] op_sel_hi:[1,0]
	v_pk_mul_f32 v[30:31], v[34:35], v[6:7] op_sel_hi:[1,0]
	s_waitcnt lgkmcnt(0)
	v_pk_mul_f32 v[12:13], v[24:25], v[12:13]
	v_pk_mul_f32 v[14:15], v[28:29], v[14:15]
	v_pk_mul_f32 v[12:13], v[12:13], v[20:21]
	v_pk_mul_f32 v[14:15], v[14:15], v[22:23]
	v_cvt_pk_bf16_f32 v12, v12, v13
	v_cvt_pk_bf16_f32 v13, v14, v15
	global_store_dwordx2 v[4:5], v[12:13], off offset:160
	ds_read_b128 v[12:15], v219 offset:352
	s_nop 0
	v_lshlrev_b32_e32 v22, 16, v246
	v_and_b32_e32 v23, 0xffff0000, v246
	v_lshlrev_b32_e32 v24, 16, v247
	v_and_b32_e32 v25, 0xffff0000, v247
	v_pk_mul_f32 v[26:27], v[38:39], v[6:7] op_sel_hi:[1,0]
	v_pk_mul_f32 v[28:29], v[36:37], v[6:7] op_sel_hi:[1,0]
	s_waitcnt lgkmcnt(0)
	v_pk_mul_f32 v[12:13], v[26:27], v[12:13]
	v_pk_mul_f32 v[14:15], v[28:29], v[14:15]
	v_pk_mul_f32 v[12:13], v[12:13], v[22:23]
	v_pk_mul_f32 v[14:15], v[14:15], v[24:25]
	v_cvt_pk_bf16_f32 v12, v12, v13
	v_cvt_pk_bf16_f32 v13, v14, v15
	global_store_dwordx2 v[4:5], v[12:13], off offset:176
	ds_read_b128 v[12:15], v219 offset:384
	s_nop 0
	v_lshlrev_b32_e32 v28, 16, v248
	v_and_b32_e32 v29, 0xffff0000, v248
	v_lshlrev_b32_e32 v20, 16, v249
	v_and_b32_e32 v21, 0xffff0000, v249
	s_waitcnt lgkmcnt(0)
	v_pk_mul_f32 v[12:13], v[30:31], v[12:13]
	v_pk_mul_f32 v[14:15], v[32:33], v[14:15]
	v_pk_mul_f32 v[12:13], v[12:13], v[28:29]
	v_pk_mul_f32 v[14:15], v[14:15], v[20:21]
	v_cvt_pk_bf16_f32 v12, v12, v13
	v_cvt_pk_bf16_f32 v13, v14, v15
	global_store_dwordx2 v[4:5], v[12:13], off offset:192
	ds_read_b128 v[12:15], v219 offset:416
	v_lshlrev_b32_e32 v20, 16, v250
	v_and_b32_e32 v21, 0xffff0000, v250
	v_lshlrev_b32_e32 v22, 16, v251
	v_and_b32_e32 v23, 0xffff0000, v251
	s_waitcnt lgkmcnt(0)
	v_pk_mul_f32 v[12:13], v[18:19], v[12:13]
	v_pk_mul_f32 v[14:15], v[16:17], v[14:15]
	v_pk_mul_f32 v[12:13], v[12:13], v[20:21]
	v_pk_mul_f32 v[14:15], v[14:15], v[22:23]
	v_cvt_pk_bf16_f32 v12, v12, v13
	v_cvt_pk_bf16_f32 v13, v14, v15
	global_store_dwordx2 v[4:5], v[12:13], off offset:208
	ds_read_b128 v[12:15], v219 offset:448
	v_lshlrev_b32_e32 v16, 16, v252
	v_and_b32_e32 v17, 0xffff0000, v252
	v_lshlrev_b32_e32 v18, 16, v253
	v_and_b32_e32 v19, 0xffff0000, v253
	s_waitcnt lgkmcnt(0)
	v_pk_mul_f32 v[8:9], v[8:9], v[12:13]
	v_pk_mul_f32 v[10:11], v[10:11], v[14:15]
	v_pk_mul_f32 v[8:9], v[8:9], v[16:17]
	v_pk_mul_f32 v[10:11], v[10:11], v[18:19]
	v_cvt_pk_bf16_f32 v8, v8, v9
	v_cvt_pk_bf16_f32 v9, v10, v11
	global_store_dwordx2 v[4:5], v[8:9], off offset:224
	ds_read_b128 v[8:11], v219 offset:480
	v_lshlrev_b32_e32 v12, 16, v254
	v_and_b32_e32 v13, 0xffff0000, v254
	v_lshlrev_b32_e32 v14, 16, v255
	v_and_b32_e32 v15, 0xffff0000, v255
	s_waitcnt lgkmcnt(0)
	v_pk_mul_f32 v[2:3], v[2:3], v[8:9]
	v_pk_mul_f32 v[0:1], v[0:1], v[10:11]
	v_pk_mul_f32 v[2:3], v[2:3], v[12:13]
	v_pk_mul_f32 v[0:1], v[0:1], v[14:15]
	v_cvt_pk_bf16_f32 v2, v2, v3
	v_cvt_pk_bf16_f32 v3, v0, v1
	global_store_dwordx2 v[4:5], v[2:3], off offset:240
	s_cbranch_scc1 .LBB0_735
	s_branch .LBB0_736
.LBB0_738:
	s_mov_b32 s36, s50

.Lat1_go:
	v_sub_f32_e32 v180, v200, v199
	v_sub_f32_e32 v198, v200, v201
	s_nop 0
	v_max3_f32 v217, v144, v145, v146
	v_max3_f32 v219, v160, v161, v162
	v_max3_f32 v221, v147, v148, v149
	v_max3_f32 v225, v163, v164, v165
	v_max3_f32 v223, v150, v151, v152
	v_max3_f32 v229, v166, v167, v168
	v_add_f32_e32 v144, v144, v180
	v_add_f32_e32 v160, v160, v198
	v_max3_f32 v217, v217, v221, v223
	v_exp_f32_e32 v144, v144
	v_exp_f32_e32 v160, v160
	v_max3_f32 v219, v219, v225, v229
	v_add_f32_e32 v145, v145, v180
	v_add_f32_e32 v161, v161, v198
	v_max3_f32 v221, v153, v154, v155
	v_exp_f32_e32 v145, v145
	v_exp_f32_e32 v161, v161
	v_max3_f32 v225, v169, v170, v171
	v_add_f32_e32 v146, v146, v180
	v_add_f32_e32 v162, v162, v198
	v_max3_f32 v223, v156, v157, v158
	v_exp_f32_e32 v146, v146
	v_exp_f32_e32 v162, v162
	v_max3_f32 v229, v172, v173, v174
	v_add_f32_e32 v147, v147, v180
	v_add_f32_e32 v163, v163, v198
	v_max3_f32 v221, v221, v223, v159
	v_exp_f32_e32 v147, v147
	v_exp_f32_e32 v163, v163
	v_max3_f32 v225, v225, v229, v175
	v_add_f32_e32 v148, v148, v180
	v_add_f32_e32 v164, v164, v198
	v_max_f32_e32 v217, v217, v221
	v_exp_f32_e32 v148, v148
	v_exp_f32_e32 v164, v164
	v_max_f32_e32 v219, v219, v225
	v_add_f32_e32 v149, v149, v180
	v_add_f32_e32 v165, v165, v198
	v_add_f32_e32 v221, v200, v217
	v_exp_f32_e32 v149, v149
	v_exp_f32_e32 v165, v165
	v_add_f32_e32 v225, v200, v219
	v_add_f32_e32 v150, v150, v180
	v_add_f32_e32 v166, v166, v198
	v_cmp_gt_f32_e32 vcc, v221, v227
	v_exp_f32_e32 v150, v150
	v_exp_f32_e32 v166, v166
	v_cmp_gt_f32_e64 s[0:1], v225, v215
	v_sub_f32_e32 v223, v221, v227
	v_sub_f32_e32 v229, v225, v215
	v_max_f32_e32 v223, v223, v229
	v_add_f32_e32 v223, 0x43280000, v223
	v_cmp_nlt_f32_e64 s[98:99], v223, 0
	v_add_f32_e32 v151, v151, v180
	v_add_f32_e32 v167, v167, v198
	v_exp_f32_e32 v151, v151
	v_exp_f32_e32 v167, v167
	v_add_f32_e32 v215, v144, v145
	v_add_f32_e32 v217, v160, v161
	v_add_f32_e32 v215, v215, v146
	v_add_f32_e32 v217, v217, v162
	v_add_f32_e32 v215, v215, v147
	v_add_f32_e32 v217, v217, v163
	v_add_f32_e32 v215, v215, v148
	v_add_f32_e32 v217, v217, v164
	v_add_f32_e32 v215, v215, v149
	v_add_f32_e32 v217, v217, v165
	v_add_f32_e32 v215, v215, v150
	v_add_f32_e32 v217, v217, v166
	v_add_f32_e32 v215, v215, v151
	v_add_f32_e32 v217, v217, v167
	v_cvt_pk_bf16_f32 v144, v144, v145
	v_cvt_pk_bf16_f32 v160, v160, v161
	v_cvt_pk_bf16_f32 v145, v146, v147
	v_cvt_pk_bf16_f32 v161, v162, v163
	v_cvt_pk_bf16_f32 v146, v148, v149
	v_cvt_pk_bf16_f32 v162, v164, v165
	v_cvt_pk_bf16_f32 v147, v150, v151
	v_cvt_pk_bf16_f32 v163, v166, v167
	ds_read_b64_tr_b16 v[148:149], v216 offset:12288
	ds_read_b64_tr_b16 v[150:151], v218 offset:12288
	ds_read_b64_tr_b16 v[164:165], v220 offset:12288
	ds_read_b64_tr_b16 v[166:167], v222 offset:12288
	s_or_b64 vcc, vcc, s[0:1]
	s_cbranch_vccnz .Lat1_redo
	s_cmp_eq_u64 s[98:99], 0
	s_cbranch_scc1 .Lat1_skip
	s_waitcnt lgkmcnt(4)
	v_mfma_f32_32x32x16_bf16 v[112:127], v[202:205], v[144:147], v[112:127]
	v_add_f32_e32 v152, v152, v180
	v_add_f32_e32 v168, v168, v198
	v_exp_f32_e32 v152, v152
	v_exp_f32_e32 v168, v168
	v_mfma_f32_32x32x16_bf16 v[96:111], v[202:205], v[160:163], v[96:111]
	v_add_f32_e32 v153, v153, v180
	v_add_f32_e32 v169, v169, v198
	v_exp_f32_e32 v153, v153
	v_exp_f32_e32 v169, v169
	ds_read_b64_tr_b16 v[202:203], v224 offset:12288
	ds_read_b64_tr_b16 v[204:205], v226 offset:12288
	v_mfma_f32_32x32x16_bf16 v[64:79], v[244:247], v[144:147], v[64:79]
	v_add_f32_e32 v154, v154, v180
	v_add_f32_e32 v170, v170, v198
	v_exp_f32_e32 v154, v154
	v_exp_f32_e32 v170, v170
	v_mfma_f32_32x32x16_bf16 v[80:95], v[244:247], v[160:163], v[80:95]
	v_add_f32_e32 v155, v155, v180
	v_add_f32_e32 v171, v171, v198
	v_exp_f32_e32 v155, v155
	v_exp_f32_e32 v171, v171
	ds_read_b64_tr_b16 v[244:245], v228 offset:12288
	ds_read_b64_tr_b16 v[246:247], v230 offset:12288
	v_mfma_f32_32x32x16_bf16 v[32:47], v[248:251], v[144:147], v[32:47]
	v_add_f32_e32 v156, v156, v180
	v_add_f32_e32 v172, v172, v198
	v_exp_f32_e32 v156, v156
	v_exp_f32_e32 v172, v172
	v_mfma_f32_32x32x16_bf16 v[48:63], v[248:251], v[160:163], v[48:63]
	v_add_f32_e32 v157, v157, v180
	v_add_f32_e32 v173, v173, v198
	v_exp_f32_e32 v157, v157
	v_exp_f32_e32 v173, v173
	v_mfma_f32_32x32x16_bf16 v[0:15], v[252:255], v[144:147], v[0:15]
	v_add_f32_e32 v158, v158, v180
	v_add_f32_e32 v174, v174, v198
	v_exp_f32_e32 v158, v158
	v_exp_f32_e32 v174, v174
	v_mfma_f32_32x32x16_bf16 v[16:31], v[252:255], v[160:163], v[16:31]
	v_add_f32_e32 v159, v159, v180
	v_add_f32_e32 v175, v175, v198
	v_exp_f32_e32 v159, v159
	v_exp_f32_e32 v175, v175
	v_cvt_pk_bf16_f32 v248, v152, v153
	v_cvt_pk_bf16_f32 v252, v168, v169
	v_cvt_pk_bf16_f32 v249, v154, v155
	v_cvt_pk_bf16_f32 v253, v170, v171
	v_cvt_pk_bf16_f32 v250, v156, v157
	v_cvt_pk_bf16_f32 v254, v172, v173
	v_cvt_pk_bf16_f32 v251, v158, v159
	v_cvt_pk_bf16_f32 v255, v174, v175
	s_nop 0
	s_waitcnt lgkmcnt(6)
	v_mfma_f32_32x32x16_bf16 v[112:127], v[148:151], v[248:251], v[112:127]
	v_add_f32_e32 v215, v215, v152
	v_add_f32_e32 v217, v217, v168
	v_mfma_f32_32x32x16_bf16 v[96:111], v[148:151], v[252:255], v[96:111]
	v_add_f32_e32 v215, v215, v153
	v_add_f32_e32 v217, v217, v169
	v_add_f32_e32 v215, v215, v154
	s_waitcnt lgkmcnt(4)
	v_mfma_f32_32x32x16_bf16 v[64:79], v[164:167], v[248:251], v[64:79]
	v_add_f32_e32 v217, v217, v170
	v_add_f32_e32 v215, v215, v155
	v_mfma_f32_32x32x16_bf16 v[80:95], v[164:167], v[252:255], v[80:95]
	v_add_f32_e32 v217, v217, v171
	v_add_f32_e32 v215, v215, v156
	v_add_f32_e32 v217, v217, v172
	s_waitcnt lgkmcnt(2)
	v_mfma_f32_32x32x16_bf16 v[32:47], v[202:205], v[248:251], v[32:47]
	v_add_f32_e32 v215, v215, v157
	v_add_f32_e32 v217, v217, v173
	v_mfma_f32_32x32x16_bf16 v[48:63], v[202:205], v[252:255], v[48:63]
	v_add_f32_e32 v215, v215, v158
	v_add_f32_e32 v217, v217, v174
	v_add_f32_e32 v215, v215, v159
	s_waitcnt lgkmcnt(0)
	v_mfma_f32_32x32x16_bf16 v[0:15], v[244:247], v[248:251], v[0:15]
	v_add_f32_e32 v217, v217, v175
	v_add_f32_e32 v197, v197, v215
	v_mfma_f32_32x32x16_bf16 v[16:31], v[244:247], v[252:255], v[16:31]
	v_add_f32_e32 v196, v196, v217
.Lat1_skip:
	s_cmp_gt_i32 s38, s84
	s_cbranch_scc1 .LBB0_759

.Lat2_go:
	v_sub_f32_e32 v180, v200, v199
	v_sub_f32_e32 v198, v200, v201
	s_nop 0
	v_max3_f32 v217, v144, v145, v146
	v_max3_f32 v219, v160, v161, v162
	v_max3_f32 v221, v147, v148, v149
	v_max3_f32 v225, v163, v164, v165
	v_max3_f32 v223, v150, v151, v152
	v_max3_f32 v229, v166, v167, v168
	v_add_f32_e32 v144, v144, v180
	v_add_f32_e32 v160, v160, v198
	v_max3_f32 v217, v217, v221, v223
	v_exp_f32_e32 v144, v144
	v_exp_f32_e32 v160, v160
	v_max3_f32 v219, v219, v225, v229
	v_add_f32_e32 v145, v145, v180
	v_add_f32_e32 v161, v161, v198
	v_max3_f32 v221, v153, v154, v155
	v_exp_f32_e32 v145, v145
	v_exp_f32_e32 v161, v161
	v_max3_f32 v225, v169, v170, v171
	v_add_f32_e32 v146, v146, v180
	v_add_f32_e32 v162, v162, v198
	v_max3_f32 v223, v156, v157, v158
	v_exp_f32_e32 v146, v146
	v_exp_f32_e32 v162, v162
	v_max3_f32 v229, v172, v173, v174
	v_add_f32_e32 v147, v147, v180
	v_add_f32_e32 v163, v163, v198
	v_max3_f32 v221, v221, v223, v159
	v_exp_f32_e32 v147, v147
	v_exp_f32_e32 v163, v163
	v_max3_f32 v225, v225, v229, v175
	v_add_f32_e32 v148, v148, v180
	v_add_f32_e32 v164, v164, v198
	v_max_f32_e32 v217, v217, v221
	v_exp_f32_e32 v148, v148
	v_exp_f32_e32 v164, v164
	v_max_f32_e32 v219, v219, v225
	v_add_f32_e32 v149, v149, v180
	v_add_f32_e32 v165, v165, v198
	v_add_f32_e32 v221, v200, v217
	v_exp_f32_e32 v149, v149
	v_exp_f32_e32 v165, v165
	v_add_f32_e32 v225, v200, v219
	v_add_f32_e32 v150, v150, v180
	v_add_f32_e32 v166, v166, v198
	v_cmp_gt_f32_e32 vcc, v221, v227
	v_exp_f32_e32 v150, v150
	v_exp_f32_e32 v166, v166
	v_cmp_gt_f32_e64 s[0:1], v225, v215
	v_sub_f32_e32 v223, v221, v227
	v_sub_f32_e32 v229, v225, v215
	v_max_f32_e32 v223, v223, v229
	v_add_f32_e32 v223, 0x43280000, v223
	v_cmp_nlt_f32_e64 s[98:99], v223, 0
	v_add_f32_e32 v151, v151, v180
	v_add_f32_e32 v167, v167, v198
	v_exp_f32_e32 v151, v151
	v_exp_f32_e32 v167, v167
	v_add_f32_e32 v215, v144, v145
	v_add_f32_e32 v217, v160, v161
	v_add_f32_e32 v215, v215, v146
	v_add_f32_e32 v217, v217, v162
	v_add_f32_e32 v215, v215, v147
	v_add_f32_e32 v217, v217, v163
	v_add_f32_e32 v215, v215, v148
	v_add_f32_e32 v217, v217, v164
	v_add_f32_e32 v215, v215, v149
	v_add_f32_e32 v217, v217, v165
	v_add_f32_e32 v215, v215, v150
	v_add_f32_e32 v217, v217, v166
	v_add_f32_e32 v215, v215, v151
	v_add_f32_e32 v217, v217, v167
	v_cvt_pk_bf16_f32 v144, v144, v145
	v_cvt_pk_bf16_f32 v160, v160, v161
	v_cvt_pk_bf16_f32 v145, v146, v147
	v_cvt_pk_bf16_f32 v161, v162, v163
	v_cvt_pk_bf16_f32 v146, v148, v149
	v_cvt_pk_bf16_f32 v162, v164, v165
	v_cvt_pk_bf16_f32 v147, v150, v151
	v_cvt_pk_bf16_f32 v163, v166, v167
	ds_read_b64_tr_b16 v[148:149], v216 offset:4096
	ds_read_b64_tr_b16 v[150:151], v218 offset:4096
	ds_read_b64_tr_b16 v[164:165], v220 offset:4096
	ds_read_b64_tr_b16 v[166:167], v222 offset:4096
	s_or_b64 vcc, vcc, s[0:1]
	s_cbranch_vccnz .Lat2_redo
	s_cmp_eq_u64 s[98:99], 0
	s_cbranch_scc1 .Lat2_skip
	s_waitcnt lgkmcnt(4)
	v_mfma_f32_32x32x16_bf16 v[112:127], v[202:205], v[144:147], v[112:127]
	v_add_f32_e32 v152, v152, v180
	v_add_f32_e32 v168, v168, v198
	v_exp_f32_e32 v152, v152
	v_exp_f32_e32 v168, v168
	v_mfma_f32_32x32x16_bf16 v[96:111], v[202:205], v[160:163], v[96:111]
	v_add_f32_e32 v153, v153, v180
	v_add_f32_e32 v169, v169, v198
	v_exp_f32_e32 v153, v153
	v_exp_f32_e32 v169, v169
	ds_read_b64_tr_b16 v[202:203], v224 offset:4096
	ds_read_b64_tr_b16 v[204:205], v226 offset:4096
	v_mfma_f32_32x32x16_bf16 v[64:79], v[244:247], v[144:147], v[64:79]
	v_add_f32_e32 v154, v154, v180
	v_add_f32_e32 v170, v170, v198
	v_exp_f32_e32 v154, v154
	v_exp_f32_e32 v170, v170
	v_mfma_f32_32x32x16_bf16 v[80:95], v[244:247], v[160:163], v[80:95]
	v_add_f32_e32 v155, v155, v180
	v_add_f32_e32 v171, v171, v198
	v_exp_f32_e32 v155, v155
	v_exp_f32_e32 v171, v171
	ds_read_b64_tr_b16 v[244:245], v228 offset:4096
	ds_read_b64_tr_b16 v[246:247], v230 offset:4096
	v_mfma_f32_32x32x16_bf16 v[32:47], v[248:251], v[144:147], v[32:47]
	v_add_f32_e32 v156, v156, v180
	v_add_f32_e32 v172, v172, v198
	v_exp_f32_e32 v156, v156
	v_exp_f32_e32 v172, v172
	v_mfma_f32_32x32x16_bf16 v[48:63], v[248:251], v[160:163], v[48:63]
	v_add_f32_e32 v157, v157, v180
	v_add_f32_e32 v173, v173, v198
	v_exp_f32_e32 v157, v157
	v_exp_f32_e32 v173, v173
	v_mfma_f32_32x32x16_bf16 v[0:15], v[252:255], v[144:147], v[0:15]
	v_add_f32_e32 v158, v158, v180
	v_add_f32_e32 v174, v174, v198
	v_exp_f32_e32 v158, v158
	v_exp_f32_e32 v174, v174
	v_mfma_f32_32x32x16_bf16 v[16:31], v[252:255], v[160:163], v[16:31]
	v_add_f32_e32 v159, v159, v180
	v_add_f32_e32 v175, v175, v198
	v_exp_f32_e32 v159, v159
	v_exp_f32_e32 v175, v175
	v_cvt_pk_bf16_f32 v248, v152, v153
	v_cvt_pk_bf16_f32 v252, v168, v169
	v_cvt_pk_bf16_f32 v249, v154, v155
	v_cvt_pk_bf16_f32 v253, v170, v171
	v_cvt_pk_bf16_f32 v250, v156, v157
	v_cvt_pk_bf16_f32 v254, v172, v173
	v_cvt_pk_bf16_f32 v251, v158, v159
	v_cvt_pk_bf16_f32 v255, v174, v175
	s_nop 0
	s_waitcnt lgkmcnt(6)
	v_mfma_f32_32x32x16_bf16 v[112:127], v[148:151], v[248:251], v[112:127]
	v_add_f32_e32 v215, v215, v152
	v_add_f32_e32 v217, v217, v168
	v_mfma_f32_32x32x16_bf16 v[96:111], v[148:151], v[252:255], v[96:111]
	v_add_f32_e32 v215, v215, v153
	v_add_f32_e32 v217, v217, v169
	v_add_f32_e32 v215, v215, v154
	s_waitcnt lgkmcnt(4)
	v_mfma_f32_32x32x16_bf16 v[64:79], v[164:167], v[248:251], v[64:79]
	v_add_f32_e32 v217, v217, v170
	v_add_f32_e32 v215, v215, v155
	v_mfma_f32_32x32x16_bf16 v[80:95], v[164:167], v[252:255], v[80:95]
	v_add_f32_e32 v217, v217, v171
	v_add_f32_e32 v215, v215, v156
	v_add_f32_e32 v217, v217, v172
	s_waitcnt lgkmcnt(2)
	v_mfma_f32_32x32x16_bf16 v[32:47], v[202:205], v[248:251], v[32:47]
	v_add_f32_e32 v215, v215, v157
	v_add_f32_e32 v217, v217, v173
	v_mfma_f32_32x32x16_bf16 v[48:63], v[202:205], v[252:255], v[48:63]
	v_add_f32_e32 v215, v215, v158
	v_add_f32_e32 v217, v217, v174
	v_add_f32_e32 v215, v215, v159
	s_waitcnt lgkmcnt(0)
	v_mfma_f32_32x32x16_bf16 v[0:15], v[244:247], v[248:251], v[0:15]
	v_add_f32_e32 v217, v217, v175
	v_add_f32_e32 v197, v197, v215
	v_mfma_f32_32x32x16_bf16 v[16:31], v[244:247], v[252:255], v[16:31]
	v_add_f32_e32 v196, v196, v217
.Lat2_skip:
	s_add_i32 s78, s41, 1
	s_cmp_ge_u32 s78, s85
	s_cbranch_scc1 .LBB0_778

.Lat3_go:
	v_sub_f32_e32 v180, v200, v199
	v_sub_f32_e32 v198, v200, v201
	s_nop 0
	v_max3_f32 v217, v144, v145, v146
	v_max3_f32 v219, v160, v161, v162
	v_max3_f32 v221, v147, v148, v149
	v_max3_f32 v225, v163, v164, v165
	v_max3_f32 v223, v150, v151, v152
	v_max3_f32 v229, v166, v167, v168
	v_add_f32_e32 v144, v144, v180
	v_add_f32_e32 v160, v160, v198
	v_max3_f32 v217, v217, v221, v223
	v_exp_f32_e32 v144, v144
	v_exp_f32_e32 v160, v160
	v_max3_f32 v219, v219, v225, v229
	v_add_f32_e32 v145, v145, v180
	v_add_f32_e32 v161, v161, v198
	v_max3_f32 v221, v153, v154, v155
	v_exp_f32_e32 v145, v145
	v_exp_f32_e32 v161, v161
	v_max3_f32 v225, v169, v170, v171
	v_add_f32_e32 v146, v146, v180
	v_add_f32_e32 v162, v162, v198
	v_max3_f32 v223, v156, v157, v158
	v_exp_f32_e32 v146, v146
	v_exp_f32_e32 v162, v162
	v_max3_f32 v229, v172, v173, v174
	v_add_f32_e32 v147, v147, v180
	v_add_f32_e32 v163, v163, v198
	v_max3_f32 v221, v221, v223, v159
	v_exp_f32_e32 v147, v147
	v_exp_f32_e32 v163, v163
	v_max3_f32 v225, v225, v229, v175
	v_add_f32_e32 v148, v148, v180
	v_add_f32_e32 v164, v164, v198
	v_max_f32_e32 v217, v217, v221
	v_exp_f32_e32 v148, v148
	v_exp_f32_e32 v164, v164
	v_max_f32_e32 v219, v219, v225
	v_add_f32_e32 v149, v149, v180
	v_add_f32_e32 v165, v165, v198
	v_add_f32_e32 v221, v200, v217
	v_exp_f32_e32 v149, v149
	v_exp_f32_e32 v165, v165
	v_add_f32_e32 v225, v200, v219
	v_add_f32_e32 v150, v150, v180
	v_add_f32_e32 v166, v166, v198
	v_cmp_gt_f32_e32 vcc, v221, v227
	v_exp_f32_e32 v150, v150
	v_exp_f32_e32 v166, v166
	v_cmp_gt_f32_e64 s[0:1], v225, v215
	v_sub_f32_e32 v223, v221, v227
	v_sub_f32_e32 v229, v225, v215
	v_max_f32_e32 v223, v223, v229
	v_add_f32_e32 v223, 0x43280000, v223
	v_cmp_nlt_f32_e64 s[98:99], v223, 0
	v_add_f32_e32 v151, v151, v180
	v_add_f32_e32 v167, v167, v198
	v_exp_f32_e32 v151, v151
	v_exp_f32_e32 v167, v167
	v_add_f32_e32 v215, v144, v145
	v_add_f32_e32 v217, v160, v161
	v_add_f32_e32 v215, v215, v146
	v_add_f32_e32 v217, v217, v162
	v_add_f32_e32 v215, v215, v147
	v_add_f32_e32 v217, v217, v163
	v_add_f32_e32 v215, v215, v148
	v_add_f32_e32 v217, v217, v164
	v_add_f32_e32 v215, v215, v149
	v_add_f32_e32 v217, v217, v165
	v_add_f32_e32 v215, v215, v150
	v_add_f32_e32 v217, v217, v166
	v_add_f32_e32 v215, v215, v151
	v_add_f32_e32 v217, v217, v167
	v_cvt_pk_bf16_f32 v144, v144, v145
	v_cvt_pk_bf16_f32 v160, v160, v161
	v_cvt_pk_bf16_f32 v145, v146, v147
	v_cvt_pk_bf16_f32 v161, v162, v163
	v_cvt_pk_bf16_f32 v146, v148, v149
	v_cvt_pk_bf16_f32 v162, v164, v165
	v_cvt_pk_bf16_f32 v147, v150, v151
	v_cvt_pk_bf16_f32 v163, v166, v167
	ds_read_b64_tr_b16 v[148:149], v216 offset:28672
	ds_read_b64_tr_b16 v[150:151], v218 offset:28672
	ds_read_b64_tr_b16 v[164:165], v220 offset:28672
	ds_read_b64_tr_b16 v[166:167], v222 offset:28672
	s_or_b64 vcc, vcc, s[0:1]
	s_cbranch_vccnz .Lat3_redo
	s_cmp_eq_u64 s[98:99], 0
	s_cbranch_scc1 .Lat3_skip
	s_waitcnt lgkmcnt(4)
	v_mfma_f32_32x32x16_bf16 v[112:127], v[202:205], v[144:147], v[112:127]
	v_add_f32_e32 v152, v152, v180
	v_add_f32_e32 v168, v168, v198
	v_exp_f32_e32 v152, v152
	v_exp_f32_e32 v168, v168
	v_mfma_f32_32x32x16_bf16 v[96:111], v[202:205], v[160:163], v[96:111]
	v_add_f32_e32 v153, v153, v180
	v_add_f32_e32 v169, v169, v198
	v_exp_f32_e32 v153, v153
	v_exp_f32_e32 v169, v169
	ds_read_b64_tr_b16 v[202:203], v224 offset:28672
	ds_read_b64_tr_b16 v[204:205], v226 offset:28672
	v_mfma_f32_32x32x16_bf16 v[64:79], v[244:247], v[144:147], v[64:79]
	v_add_f32_e32 v154, v154, v180
	v_add_f32_e32 v170, v170, v198
	v_exp_f32_e32 v154, v154
	v_exp_f32_e32 v170, v170
	v_mfma_f32_32x32x16_bf16 v[80:95], v[244:247], v[160:163], v[80:95]
	v_add_f32_e32 v155, v155, v180
	v_add_f32_e32 v171, v171, v198
	v_exp_f32_e32 v155, v155
	v_exp_f32_e32 v171, v171
	ds_read_b64_tr_b16 v[244:245], v228 offset:28672
	ds_read_b64_tr_b16 v[246:247], v230 offset:28672
	v_mfma_f32_32x32x16_bf16 v[32:47], v[248:251], v[144:147], v[32:47]
	v_add_f32_e32 v156, v156, v180
	v_add_f32_e32 v172, v172, v198
	v_exp_f32_e32 v156, v156
	v_exp_f32_e32 v172, v172
	v_mfma_f32_32x32x16_bf16 v[48:63], v[248:251], v[160:163], v[48:63]
	v_add_f32_e32 v157, v157, v180
	v_add_f32_e32 v173, v173, v198
	v_exp_f32_e32 v157, v157
	v_exp_f32_e32 v173, v173
	v_mfma_f32_32x32x16_bf16 v[0:15], v[252:255], v[144:147], v[0:15]
	v_add_f32_e32 v158, v158, v180
	v_add_f32_e32 v174, v174, v198
	v_exp_f32_e32 v158, v158
	v_exp_f32_e32 v174, v174
	v_mfma_f32_32x32x16_bf16 v[16:31], v[252:255], v[160:163], v[16:31]
	v_add_f32_e32 v159, v159, v180
	v_add_f32_e32 v175, v175, v198
	v_exp_f32_e32 v159, v159
	v_exp_f32_e32 v175, v175
	v_cvt_pk_bf16_f32 v248, v152, v153
	v_cvt_pk_bf16_f32 v252, v168, v169
	v_cvt_pk_bf16_f32 v249, v154, v155
	v_cvt_pk_bf16_f32 v253, v170, v171
	v_cvt_pk_bf16_f32 v250, v156, v157
	v_cvt_pk_bf16_f32 v254, v172, v173
	v_cvt_pk_bf16_f32 v251, v158, v159
	v_cvt_pk_bf16_f32 v255, v174, v175
	s_nop 0
	s_waitcnt lgkmcnt(6)
	v_mfma_f32_32x32x16_bf16 v[112:127], v[148:151], v[248:251], v[112:127]
	v_add_f32_e32 v215, v215, v152
	v_add_f32_e32 v217, v217, v168
	v_mfma_f32_32x32x16_bf16 v[96:111], v[148:151], v[252:255], v[96:111]
	v_add_f32_e32 v215, v215, v153
	v_add_f32_e32 v217, v217, v169
	v_add_f32_e32 v215, v215, v154
	s_waitcnt lgkmcnt(4)
	v_mfma_f32_32x32x16_bf16 v[64:79], v[164:167], v[248:251], v[64:79]
	v_add_f32_e32 v217, v217, v170
	v_add_f32_e32 v215, v215, v155
	v_mfma_f32_32x32x16_bf16 v[80:95], v[164:167], v[252:255], v[80:95]
	v_add_f32_e32 v217, v217, v171
	v_add_f32_e32 v215, v215, v156
	v_add_f32_e32 v217, v217, v172
	s_waitcnt lgkmcnt(2)
	v_mfma_f32_32x32x16_bf16 v[32:47], v[202:205], v[248:251], v[32:47]
	v_add_f32_e32 v215, v215, v157
	v_add_f32_e32 v217, v217, v173
	v_mfma_f32_32x32x16_bf16 v[48:63], v[202:205], v[252:255], v[48:63]
	v_add_f32_e32 v215, v215, v158
	v_add_f32_e32 v217, v217, v174
	v_add_f32_e32 v215, v215, v159
	s_waitcnt lgkmcnt(0)
	v_mfma_f32_32x32x16_bf16 v[0:15], v[244:247], v[248:251], v[0:15]
	v_add_f32_e32 v217, v217, v175
	v_add_f32_e32 v197, v197, v215
	v_mfma_f32_32x32x16_bf16 v[16:31], v[244:247], v[252:255], v[16:31]
	v_add_f32_e32 v196, v196, v217
.Lat3_skip:
	s_cmp_gt_i32 s78, s84
	s_cbranch_scc1 .LBB0_778
.LBB0_792:
	ds_read_b128 v[160:163], v237 offset:16384
	ds_read_b128 v[164:167], v189
	ds_read_b128 v[202:205], v235 offset:16384
	ds_read_b128 v[244:247], v189 offset:4096
	ds_read_b128 v[248:251], v236 offset:16384
	ds_read_b128 v[252:255], v189 offset:1024
	s_cmp_lg_u32 s39, s40
	s_waitcnt lgkmcnt(4)
	v_mfma_f32_32x32x16_bf16 v[144:159], v[160:163], v[164:167], v[128:143]
	s_waitcnt lgkmcnt(2)
	v_mfma_f32_32x32x16_bf16 v[160:175], v[202:205], v[244:247], v[128:143]
	ds_read_b128 v[202:205], v234 offset:16384
	ds_read_b128 v[244:247], v189 offset:5120
	v_add_u32_e32 v215, s40, v185
	v_add_u32_e32 v215, 0x80, v215
	v_cvt_f32_i32_e32 v215, v215
	v_add_f32_e32 v227, 0x41000000, v199
	v_mul_f32_e32 v200, v184, v215
	v_add_f32_e32 v215, 0x41000000, v201
	s_waitcnt lgkmcnt(2)
	v_mfma_f32_32x32x16_bf16 v[144:159], v[248:251], v[252:255], v[144:159]
	ds_read_b128 v[248:251], v241 offset:16384
	ds_read_b128 v[252:255], v189 offset:2048
	s_waitcnt lgkmcnt(2)
	v_mfma_f32_32x32x16_bf16 v[160:175], v[202:205], v[244:247], v[160:175]
	ds_read_b128 v[202:205], v239 offset:16384
	ds_read_b128 v[244:247], v189 offset:6144
	s_waitcnt lgkmcnt(2)
	v_mfma_f32_32x32x16_bf16 v[144:159], v[248:251], v[252:255], v[144:159]
	ds_read_b128 v[248:251], v240 offset:16384
	ds_read_b128 v[252:255], v189 offset:3072
	s_waitcnt lgkmcnt(2)
	v_mfma_f32_32x32x16_bf16 v[160:175], v[202:205], v[244:247], v[160:175]
	ds_read_b128 v[202:205], v238 offset:16384
	ds_read_b128 v[244:247], v189 offset:7168
	s_waitcnt lgkmcnt(2)
	v_mfma_f32_32x32x16_bf16 v[144:159], v[248:251], v[252:255], v[144:159]
	s_waitcnt lgkmcnt(0)
	v_mfma_f32_32x32x16_bf16 v[160:175], v[202:205], v[244:247], v[160:175]
	ds_read_b64_tr_b16 v[202:203], v216 offset:16384
	ds_read_b64_tr_b16 v[204:205], v218 offset:16384
	ds_read_b64_tr_b16 v[244:245], v220 offset:16384
	ds_read_b64_tr_b16 v[246:247], v222 offset:16384
	ds_read_b64_tr_b16 v[248:249], v224 offset:16384
	ds_read_b64_tr_b16 v[250:251], v226 offset:16384
	ds_read_b64_tr_b16 v[252:253], v228 offset:16384
	ds_read_b64_tr_b16 v[254:255], v230 offset:16384
	s_cbranch_scc0 .Lat4_diag
.Lat4_go:
	v_sub_f32_e32 v180, v200, v199
	v_sub_f32_e32 v198, v200, v201
	s_nop 0
	v_max3_f32 v217, v144, v145, v146
	v_max3_f32 v219, v160, v161, v162
	v_max3_f32 v221, v147, v148, v149
	v_max3_f32 v225, v163, v164, v165
	v_max3_f32 v223, v150, v151, v152
	v_max3_f32 v229, v166, v167, v168
	v_add_f32_e32 v144, v144, v180
	v_add_f32_e32 v160, v160, v198
	v_max3_f32 v217, v217, v221, v223
	v_exp_f32_e32 v144, v144
	v_exp_f32_e32 v160, v160
	v_max3_f32 v219, v219, v225, v229
	v_add_f32_e32 v145, v145, v180
	v_add_f32_e32 v161, v161, v198
	v_max3_f32 v221, v153, v154, v155
	v_exp_f32_e32 v145, v145
	v_exp_f32_e32 v161, v161
	v_max3_f32 v225, v169, v170, v171
	v_add_f32_e32 v146, v146, v180
	v_add_f32_e32 v162, v162, v198
	v_max3_f32 v223, v156, v157, v158
	v_exp_f32_e32 v146, v146
	v_exp_f32_e32 v162, v162
	v_max3_f32 v229, v172, v173, v174
	v_add_f32_e32 v147, v147, v180
	v_add_f32_e32 v163, v163, v198
	v_max3_f32 v221, v221, v223, v159
	v_exp_f32_e32 v147, v147
	v_exp_f32_e32 v163, v163
	v_max3_f32 v225, v225, v229, v175
	v_add_f32_e32 v148, v148, v180
	v_add_f32_e32 v164, v164, v198
	v_max_f32_e32 v217, v217, v221
	v_exp_f32_e32 v148, v148
	v_exp_f32_e32 v164, v164
	v_max_f32_e32 v219, v219, v225
	v_add_f32_e32 v149, v149, v180
	v_add_f32_e32 v165, v165, v198
	v_add_f32_e32 v221, v200, v217
	v_exp_f32_e32 v149, v149
	v_exp_f32_e32 v165, v165
	v_add_f32_e32 v225, v200, v219
	v_add_f32_e32 v150, v150, v180
	v_add_f32_e32 v166, v166, v198
	v_cmp_gt_f32_e32 vcc, v221, v227
	v_exp_f32_e32 v150, v150
	v_exp_f32_e32 v166, v166
	v_cmp_gt_f32_e64 s[0:1], v225, v215
	v_sub_f32_e32 v223, v221, v227
	v_sub_f32_e32 v229, v225, v215
	v_max_f32_e32 v223, v223, v229
	v_add_f32_e32 v223, 0x43280000, v223
	v_cmp_nlt_f32_e64 s[98:99], v223, 0
	v_add_f32_e32 v151, v151, v180
	v_add_f32_e32 v167, v167, v198
	v_exp_f32_e32 v151, v151
	v_exp_f32_e32 v167, v167
	v_add_f32_e32 v215, v144, v145
	v_add_f32_e32 v217, v160, v161
	v_add_f32_e32 v215, v215, v146
	v_add_f32_e32 v217, v217, v162
	v_add_f32_e32 v215, v215, v147
	v_add_f32_e32 v217, v217, v163
	v_add_f32_e32 v215, v215, v148
	v_add_f32_e32 v217, v217, v164
	v_add_f32_e32 v215, v215, v149
	v_add_f32_e32 v217, v217, v165
	v_add_f32_e32 v215, v215, v150
	v_add_f32_e32 v217, v217, v166
	v_add_f32_e32 v215, v215, v151
	v_add_f32_e32 v217, v217, v167
	v_cvt_pk_bf16_f32 v144, v144, v145
	v_cvt_pk_bf16_f32 v160, v160, v161
	v_cvt_pk_bf16_f32 v145, v146, v147
	v_cvt_pk_bf16_f32 v161, v162, v163
	v_cvt_pk_bf16_f32 v146, v148, v149
	v_cvt_pk_bf16_f32 v162, v164, v165
	v_cvt_pk_bf16_f32 v147, v150, v151
	v_cvt_pk_bf16_f32 v163, v166, v167
	ds_read_b64_tr_b16 v[148:149], v216 offset:20480
	ds_read_b64_tr_b16 v[150:151], v218 offset:20480
	ds_read_b64_tr_b16 v[164:165], v220 offset:20480
	ds_read_b64_tr_b16 v[166:167], v222 offset:20480
	s_or_b64 vcc, vcc, s[0:1]
	s_cbranch_vccnz .Lat4_redo
	s_cmp_eq_u64 s[98:99], 0
	s_cbranch_scc1 .Lat4_skip
	s_waitcnt lgkmcnt(4)
	v_mfma_f32_32x32x16_bf16 v[112:127], v[202:205], v[144:147], v[112:127]
	v_add_f32_e32 v152, v152, v180
	v_add_f32_e32 v168, v168, v198
	v_exp_f32_e32 v152, v152
	v_exp_f32_e32 v168, v168
	v_mfma_f32_32x32x16_bf16 v[96:111], v[202:205], v[160:163], v[96:111]
	v_add_f32_e32 v153, v153, v180
	v_add_f32_e32 v169, v169, v198
	v_exp_f32_e32 v153, v153
	v_exp_f32_e32 v169, v169
	ds_read_b64_tr_b16 v[202:203], v224 offset:20480
	ds_read_b64_tr_b16 v[204:205], v226 offset:20480
	v_mfma_f32_32x32x16_bf16 v[64:79], v[244:247], v[144:147], v[64:79]
	v_add_f32_e32 v154, v154, v180
	v_add_f32_e32 v170, v170, v198
	v_exp_f32_e32 v154, v154
	v_exp_f32_e32 v170, v170
	v_mfma_f32_32x32x16_bf16 v[80:95], v[244:247], v[160:163], v[80:95]
	v_add_f32_e32 v155, v155, v180
	v_add_f32_e32 v171, v171, v198
	v_exp_f32_e32 v155, v155
	v_exp_f32_e32 v171, v171
	ds_read_b64_tr_b16 v[244:245], v228 offset:20480
	ds_read_b64_tr_b16 v[246:247], v230 offset:20480
	v_mfma_f32_32x32x16_bf16 v[32:47], v[248:251], v[144:147], v[32:47]
	v_add_f32_e32 v156, v156, v180
	v_add_f32_e32 v172, v172, v198
	v_exp_f32_e32 v156, v156
	v_exp_f32_e32 v172, v172
	v_mfma_f32_32x32x16_bf16 v[48:63], v[248:251], v[160:163], v[48:63]
	v_add_f32_e32 v157, v157, v180
	v_add_f32_e32 v173, v173, v198
	v_exp_f32_e32 v157, v157
	v_exp_f32_e32 v173, v173
	v_mfma_f32_32x32x16_bf16 v[0:15], v[252:255], v[144:147], v[0:15]
	v_add_f32_e32 v158, v158, v180
	v_add_f32_e32 v174, v174, v198
	v_exp_f32_e32 v158, v158
	v_exp_f32_e32 v174, v174
	v_mfma_f32_32x32x16_bf16 v[16:31], v[252:255], v[160:163], v[16:31]
	v_add_f32_e32 v159, v159, v180
	v_add_f32_e32 v175, v175, v198
	v_exp_f32_e32 v159, v159
	v_exp_f32_e32 v175, v175
	v_cvt_pk_bf16_f32 v248, v152, v153
	v_cvt_pk_bf16_f32 v252, v168, v169
	v_cvt_pk_bf16_f32 v249, v154, v155
	v_cvt_pk_bf16_f32 v253, v170, v171
	v_cvt_pk_bf16_f32 v250, v156, v157
	v_cvt_pk_bf16_f32 v254, v172, v173
	v_cvt_pk_bf16_f32 v251, v158, v159
	v_cvt_pk_bf16_f32 v255, v174, v175
	s_nop 0
	s_waitcnt lgkmcnt(6)
	v_mfma_f32_32x32x16_bf16 v[112:127], v[148:151], v[248:251], v[112:127]
	v_add_f32_e32 v215, v215, v152
	v_add_f32_e32 v217, v217, v168
	v_mfma_f32_32x32x16_bf16 v[96:111], v[148:151], v[252:255], v[96:111]
	v_add_f32_e32 v215, v215, v153
	v_add_f32_e32 v217, v217, v169
	v_add_f32_e32 v215, v215, v154
	s_waitcnt lgkmcnt(4)
	v_mfma_f32_32x32x16_bf16 v[64:79], v[164:167], v[248:251], v[64:79]
	v_add_f32_e32 v217, v217, v170
	v_add_f32_e32 v215, v215, v155
	v_mfma_f32_32x32x16_bf16 v[80:95], v[164:167], v[252:255], v[80:95]
	v_add_f32_e32 v217, v217, v171
	v_add_f32_e32 v215, v215, v156
	v_add_f32_e32 v217, v217, v172
	s_waitcnt lgkmcnt(2)
	v_mfma_f32_32x32x16_bf16 v[32:47], v[202:205], v[248:251], v[32:47]
	v_add_f32_e32 v215, v215, v157
	v_add_f32_e32 v217, v217, v173
	v_mfma_f32_32x32x16_bf16 v[48:63], v[202:205], v[252:255], v[48:63]
	v_add_f32_e32 v215, v215, v158
	v_add_f32_e32 v217, v217, v174
	v_add_f32_e32 v215, v215, v159
	s_waitcnt lgkmcnt(0)
	v_mfma_f32_32x32x16_bf16 v[0:15], v[244:247], v[248:251], v[0:15]
	v_add_f32_e32 v217, v217, v175
	v_add_f32_e32 v197, v197, v215
	v_mfma_f32_32x32x16_bf16 v[16:31], v[244:247], v[252:255], v[16:31]
	v_add_f32_e32 v196, v196, v217
.Lat4_skip:
	s_add_i32 s0, s41, 2
	s_cmp_ge_u32 s0, s85
	s_cbranch_scc1 .LBB0_753
	s_branch .LBB0_779

.Lat5_go:
	v_sub_f32_e32 v180, v200, v199
	v_sub_f32_e32 v198, v200, v201
	s_nop 0
	v_max3_f32 v217, v144, v145, v146
	v_max3_f32 v219, v160, v161, v162
	v_max3_f32 v221, v147, v148, v149
	v_max3_f32 v225, v163, v164, v165
	v_max3_f32 v223, v150, v151, v152
	v_max3_f32 v229, v166, v167, v168
	v_add_f32_e32 v144, v144, v180
	v_add_f32_e32 v160, v160, v198
	v_max3_f32 v217, v217, v221, v223
	v_exp_f32_e32 v144, v144
	v_exp_f32_e32 v160, v160
	v_max3_f32 v219, v219, v225, v229
	v_add_f32_e32 v145, v145, v180
	v_add_f32_e32 v161, v161, v198
	v_max3_f32 v221, v153, v154, v155
	v_exp_f32_e32 v145, v145
	v_exp_f32_e32 v161, v161
	v_max3_f32 v225, v169, v170, v171
	v_add_f32_e32 v146, v146, v180
	v_add_f32_e32 v162, v162, v198
	v_max3_f32 v223, v156, v157, v158
	v_exp_f32_e32 v146, v146
	v_exp_f32_e32 v162, v162
	v_max3_f32 v229, v172, v173, v174
	v_add_f32_e32 v147, v147, v180
	v_add_f32_e32 v163, v163, v198
	v_max3_f32 v221, v221, v223, v159
	v_exp_f32_e32 v147, v147
	v_exp_f32_e32 v163, v163
	v_max3_f32 v225, v225, v229, v175
	v_add_f32_e32 v148, v148, v180
	v_add_f32_e32 v164, v164, v198
	v_max_f32_e32 v217, v217, v221
	v_exp_f32_e32 v148, v148
	v_exp_f32_e32 v164, v164
	v_max_f32_e32 v219, v219, v225
	v_add_f32_e32 v149, v149, v180
	v_add_f32_e32 v165, v165, v198
	v_add_f32_e32 v221, v200, v217
	v_exp_f32_e32 v149, v149
	v_exp_f32_e32 v165, v165
	v_add_f32_e32 v225, v200, v219
	v_add_f32_e32 v150, v150, v180
	v_add_f32_e32 v166, v166, v198
	v_cmp_gt_f32_e32 vcc, v221, v227
	v_exp_f32_e32 v150, v150
	v_exp_f32_e32 v166, v166
	v_cmp_gt_f32_e64 s[0:1], v225, v215
	v_sub_f32_e32 v223, v221, v227
	v_sub_f32_e32 v229, v225, v215
	v_max_f32_e32 v223, v223, v229
	v_add_f32_e32 v223, 0x43280000, v223
	v_cmp_nlt_f32_e64 s[98:99], v223, 0
	v_add_f32_e32 v151, v151, v180
	v_add_f32_e32 v167, v167, v198
	v_exp_f32_e32 v151, v151
	v_exp_f32_e32 v167, v167
	v_add_f32_e32 v215, v144, v145
	v_add_f32_e32 v217, v160, v161
	v_add_f32_e32 v215, v215, v146
	v_add_f32_e32 v217, v217, v162
	v_add_f32_e32 v215, v215, v147
	v_add_f32_e32 v217, v217, v163
	v_add_f32_e32 v215, v215, v148
	v_add_f32_e32 v217, v217, v164
	v_add_f32_e32 v215, v215, v149
	v_add_f32_e32 v217, v217, v165
	v_add_f32_e32 v215, v215, v150
	v_add_f32_e32 v217, v217, v166
	v_add_f32_e32 v215, v215, v151
	v_add_f32_e32 v217, v217, v167
	v_cvt_pk_bf16_f32 v144, v144, v145
	v_cvt_pk_bf16_f32 v160, v160, v161
	v_cvt_pk_bf16_f32 v145, v146, v147
	v_cvt_pk_bf16_f32 v161, v162, v163
	v_cvt_pk_bf16_f32 v146, v148, v149
	v_cvt_pk_bf16_f32 v162, v164, v165
	v_cvt_pk_bf16_f32 v147, v150, v151
	v_cvt_pk_bf16_f32 v163, v166, v167
	ds_read_b64_tr_b16 v[148:149], v216 offset:45056
	ds_read_b64_tr_b16 v[150:151], v218 offset:45056
	ds_read_b64_tr_b16 v[164:165], v220 offset:45056
	ds_read_b64_tr_b16 v[166:167], v222 offset:45056
	s_or_b64 vcc, vcc, s[0:1]
	s_cbranch_vccnz .Lat5_redo
	s_cmp_eq_u64 s[98:99], 0
	s_cbranch_scc1 .Lat5_skip
	s_waitcnt lgkmcnt(4)
	v_mfma_f32_32x32x16_bf16 v[112:127], v[202:205], v[144:147], v[112:127]
	v_add_f32_e32 v152, v152, v180
	v_add_f32_e32 v168, v168, v198
	v_exp_f32_e32 v152, v152
	v_exp_f32_e32 v168, v168
	v_mfma_f32_32x32x16_bf16 v[96:111], v[202:205], v[160:163], v[96:111]
	v_add_f32_e32 v153, v153, v180
	v_add_f32_e32 v169, v169, v198
	v_exp_f32_e32 v153, v153
	v_exp_f32_e32 v169, v169
	ds_read_b64_tr_b16 v[202:203], v224 offset:45056
	ds_read_b64_tr_b16 v[204:205], v226 offset:45056
	v_mfma_f32_32x32x16_bf16 v[64:79], v[244:247], v[144:147], v[64:79]
	v_add_f32_e32 v154, v154, v180
	v_add_f32_e32 v170, v170, v198
	v_exp_f32_e32 v154, v154
	v_exp_f32_e32 v170, v170
	v_mfma_f32_32x32x16_bf16 v[80:95], v[244:247], v[160:163], v[80:95]
	v_add_f32_e32 v155, v155, v180
	v_add_f32_e32 v171, v171, v198
	v_exp_f32_e32 v155, v155
	v_exp_f32_e32 v171, v171
	ds_read_b64_tr_b16 v[244:245], v228 offset:45056
	ds_read_b64_tr_b16 v[246:247], v230 offset:45056
	v_mfma_f32_32x32x16_bf16 v[32:47], v[248:251], v[144:147], v[32:47]
	v_add_f32_e32 v156, v156, v180
	v_add_f32_e32 v172, v172, v198
	v_exp_f32_e32 v156, v156
	v_exp_f32_e32 v172, v172
	v_mfma_f32_32x32x16_bf16 v[48:63], v[248:251], v[160:163], v[48:63]
	v_add_f32_e32 v157, v157, v180
	v_add_f32_e32 v173, v173, v198
	v_exp_f32_e32 v157, v157
	v_exp_f32_e32 v173, v173
	v_mfma_f32_32x32x16_bf16 v[0:15], v[252:255], v[144:147], v[0:15]
	v_add_f32_e32 v158, v158, v180
	v_add_f32_e32 v174, v174, v198
	v_exp_f32_e32 v158, v158
	v_exp_f32_e32 v174, v174
	v_mfma_f32_32x32x16_bf16 v[16:31], v[252:255], v[160:163], v[16:31]
	v_add_f32_e32 v159, v159, v180
	v_add_f32_e32 v175, v175, v198
	v_exp_f32_e32 v159, v159
	v_exp_f32_e32 v175, v175
	v_cvt_pk_bf16_f32 v248, v152, v153
	v_cvt_pk_bf16_f32 v252, v168, v169
	v_cvt_pk_bf16_f32 v249, v154, v155
	v_cvt_pk_bf16_f32 v253, v170, v171
	v_cvt_pk_bf16_f32 v250, v156, v157
	v_cvt_pk_bf16_f32 v254, v172, v173
	v_cvt_pk_bf16_f32 v251, v158, v159
	v_cvt_pk_bf16_f32 v255, v174, v175
	s_nop 0
	s_waitcnt lgkmcnt(6)
	v_mfma_f32_32x32x16_bf16 v[112:127], v[148:151], v[248:251], v[112:127]
	v_add_f32_e32 v215, v215, v152
	v_add_f32_e32 v217, v217, v168
	v_mfma_f32_32x32x16_bf16 v[96:111], v[148:151], v[252:255], v[96:111]
	v_add_f32_e32 v215, v215, v153
	v_add_f32_e32 v217, v217, v169
	v_add_f32_e32 v215, v215, v154
	s_waitcnt lgkmcnt(4)
	v_mfma_f32_32x32x16_bf16 v[64:79], v[164:167], v[248:251], v[64:79]
	v_add_f32_e32 v217, v217, v170
	v_add_f32_e32 v215, v215, v155
	v_mfma_f32_32x32x16_bf16 v[80:95], v[164:167], v[252:255], v[80:95]
	v_add_f32_e32 v217, v217, v171
	v_add_f32_e32 v215, v215, v156
	v_add_f32_e32 v217, v217, v172
	s_waitcnt lgkmcnt(2)
	v_mfma_f32_32x32x16_bf16 v[32:47], v[202:205], v[248:251], v[32:47]
	v_add_f32_e32 v215, v215, v157
	v_add_f32_e32 v217, v217, v173
	v_mfma_f32_32x32x16_bf16 v[48:63], v[202:205], v[252:255], v[48:63]
	v_add_f32_e32 v215, v215, v158
	v_add_f32_e32 v217, v217, v174
	v_add_f32_e32 v215, v215, v159
	s_waitcnt lgkmcnt(0)
	v_mfma_f32_32x32x16_bf16 v[0:15], v[244:247], v[248:251], v[0:15]
	v_add_f32_e32 v217, v217, v175
	v_add_f32_e32 v197, v197, v215
	v_mfma_f32_32x32x16_bf16 v[16:31], v[244:247], v[252:255], v[16:31]
	v_add_f32_e32 v196, v196, v217
.Lat5_skip:
	s_cmp_gt_i32 s78, s84
	s_cbranch_scc1 .LBB0_753
.LBB0_805:
	ds_read_b128 v[160:163], v237 offset:32768
	ds_read_b128 v[164:167], v189
	ds_read_b128 v[202:205], v235 offset:32768
	ds_read_b128 v[244:247], v189 offset:4096
	ds_read_b128 v[248:251], v236 offset:32768
	ds_read_b128 v[252:255], v189 offset:1024
	s_cmp_lg_u32 s97, s40
	s_waitcnt lgkmcnt(4)
	v_mfma_f32_32x32x16_bf16 v[144:159], v[160:163], v[164:167], v[128:143]
	s_waitcnt lgkmcnt(2)
	v_mfma_f32_32x32x16_bf16 v[160:175], v[202:205], v[244:247], v[128:143]
	ds_read_b128 v[202:205], v234 offset:32768
	ds_read_b128 v[244:247], v189 offset:5120
	v_add_u32_e32 v215, s40, v185
	v_add_u32_e32 v215, 0x40, v215
	v_cvt_f32_i32_e32 v215, v215
	v_add_f32_e32 v227, 0x41000000, v199
	v_mul_f32_e32 v200, v184, v215
	v_add_f32_e32 v215, 0x41000000, v201
	s_waitcnt lgkmcnt(2)
	v_mfma_f32_32x32x16_bf16 v[144:159], v[248:251], v[252:255], v[144:159]
	ds_read_b128 v[248:251], v241 offset:32768
	ds_read_b128 v[252:255], v189 offset:2048
	s_waitcnt lgkmcnt(2)
	v_mfma_f32_32x32x16_bf16 v[160:175], v[202:205], v[244:247], v[160:175]
	ds_read_b128 v[202:205], v239 offset:32768
	ds_read_b128 v[244:247], v189 offset:6144
	s_waitcnt lgkmcnt(2)
	v_mfma_f32_32x32x16_bf16 v[144:159], v[248:251], v[252:255], v[144:159]
	ds_read_b128 v[248:251], v240 offset:32768
	ds_read_b128 v[252:255], v189 offset:3072
	s_waitcnt lgkmcnt(2)
	v_mfma_f32_32x32x16_bf16 v[160:175], v[202:205], v[244:247], v[160:175]
	ds_read_b128 v[202:205], v238 offset:32768
	ds_read_b128 v[244:247], v189 offset:7168
	s_waitcnt lgkmcnt(2)
	v_mfma_f32_32x32x16_bf16 v[144:159], v[248:251], v[252:255], v[144:159]
	s_waitcnt lgkmcnt(0)
	v_mfma_f32_32x32x16_bf16 v[160:175], v[202:205], v[244:247], v[160:175]
	ds_read_b64_tr_b16 v[202:203], v216 offset:32768
	ds_read_b64_tr_b16 v[204:205], v218 offset:32768
	ds_read_b64_tr_b16 v[244:245], v220 offset:32768
	ds_read_b64_tr_b16 v[246:247], v222 offset:32768
	ds_read_b64_tr_b16 v[248:249], v224 offset:32768
	ds_read_b64_tr_b16 v[250:251], v226 offset:32768
	ds_read_b64_tr_b16 v[252:253], v228 offset:32768
	ds_read_b64_tr_b16 v[254:255], v230 offset:32768
	s_cbranch_scc0 .Lat6_diag
.Lat6_go:
	v_sub_f32_e32 v180, v200, v199
	v_sub_f32_e32 v198, v200, v201
	s_nop 0
	v_max3_f32 v217, v144, v145, v146
	v_max3_f32 v219, v160, v161, v162
	v_max3_f32 v221, v147, v148, v149
	v_max3_f32 v225, v163, v164, v165
	v_max3_f32 v223, v150, v151, v152
	v_max3_f32 v229, v166, v167, v168
	v_add_f32_e32 v144, v144, v180
	v_add_f32_e32 v160, v160, v198
	v_max3_f32 v217, v217, v221, v223
	v_exp_f32_e32 v144, v144
	v_exp_f32_e32 v160, v160
	v_max3_f32 v219, v219, v225, v229
	v_add_f32_e32 v145, v145, v180
	v_add_f32_e32 v161, v161, v198
	v_max3_f32 v221, v153, v154, v155
	v_exp_f32_e32 v145, v145
	v_exp_f32_e32 v161, v161
	v_max3_f32 v225, v169, v170, v171
	v_add_f32_e32 v146, v146, v180
	v_add_f32_e32 v162, v162, v198
	v_max3_f32 v223, v156, v157, v158
	v_exp_f32_e32 v146, v146
	v_exp_f32_e32 v162, v162
	v_max3_f32 v229, v172, v173, v174
	v_add_f32_e32 v147, v147, v180
	v_add_f32_e32 v163, v163, v198
	v_max3_f32 v221, v221, v223, v159
	v_exp_f32_e32 v147, v147
	v_exp_f32_e32 v163, v163
	v_max3_f32 v225, v225, v229, v175
	v_add_f32_e32 v148, v148, v180
	v_add_f32_e32 v164, v164, v198
	v_max_f32_e32 v217, v217, v221
	v_exp_f32_e32 v148, v148
	v_exp_f32_e32 v164, v164
	v_max_f32_e32 v219, v219, v225
	v_add_f32_e32 v149, v149, v180
	v_add_f32_e32 v165, v165, v198
	v_add_f32_e32 v221, v200, v217
	v_exp_f32_e32 v149, v149
	v_exp_f32_e32 v165, v165
	v_add_f32_e32 v225, v200, v219
	v_add_f32_e32 v150, v150, v180
	v_add_f32_e32 v166, v166, v198
	v_cmp_gt_f32_e32 vcc, v221, v227
	v_exp_f32_e32 v150, v150
	v_exp_f32_e32 v166, v166
	v_cmp_gt_f32_e64 s[0:1], v225, v215
	v_sub_f32_e32 v223, v221, v227
	v_sub_f32_e32 v229, v225, v215
	v_max_f32_e32 v223, v223, v229
	v_add_f32_e32 v223, 0x43280000, v223
	v_cmp_nlt_f32_e64 s[98:99], v223, 0
	v_add_f32_e32 v151, v151, v180
	v_add_f32_e32 v167, v167, v198
	v_exp_f32_e32 v151, v151
	v_exp_f32_e32 v167, v167
	v_add_f32_e32 v215, v144, v145
	v_add_f32_e32 v217, v160, v161
	v_add_f32_e32 v215, v215, v146
	v_add_f32_e32 v217, v217, v162
	v_add_f32_e32 v215, v215, v147
	v_add_f32_e32 v217, v217, v163
	v_add_f32_e32 v215, v215, v148
	v_add_f32_e32 v217, v217, v164
	v_add_f32_e32 v215, v215, v149
	v_add_f32_e32 v217, v217, v165
	v_add_f32_e32 v215, v215, v150
	v_add_f32_e32 v217, v217, v166
	v_add_f32_e32 v215, v215, v151
	v_add_f32_e32 v217, v217, v167
	v_cvt_pk_bf16_f32 v144, v144, v145
	v_cvt_pk_bf16_f32 v160, v160, v161
	v_cvt_pk_bf16_f32 v145, v146, v147
	v_cvt_pk_bf16_f32 v161, v162, v163
	v_cvt_pk_bf16_f32 v146, v148, v149
	v_cvt_pk_bf16_f32 v162, v164, v165
	v_cvt_pk_bf16_f32 v147, v150, v151
	v_cvt_pk_bf16_f32 v163, v166, v167
	ds_read_b64_tr_b16 v[148:149], v216 offset:36864
	ds_read_b64_tr_b16 v[150:151], v218 offset:36864
	ds_read_b64_tr_b16 v[164:165], v220 offset:36864
	ds_read_b64_tr_b16 v[166:167], v222 offset:36864
	s_or_b64 vcc, vcc, s[0:1]
	s_cbranch_vccnz .Lat6_redo
	s_cmp_eq_u64 s[98:99], 0
	s_cbranch_scc1 .Lat6_skip
	s_waitcnt lgkmcnt(4)
	v_mfma_f32_32x32x16_bf16 v[112:127], v[202:205], v[144:147], v[112:127]
	v_add_f32_e32 v152, v152, v180
	v_add_f32_e32 v168, v168, v198
	v_exp_f32_e32 v152, v152
	v_exp_f32_e32 v168, v168
	v_mfma_f32_32x32x16_bf16 v[96:111], v[202:205], v[160:163], v[96:111]
	v_add_f32_e32 v153, v153, v180
	v_add_f32_e32 v169, v169, v198
	v_exp_f32_e32 v153, v153
	v_exp_f32_e32 v169, v169
	ds_read_b64_tr_b16 v[202:203], v224 offset:36864
	ds_read_b64_tr_b16 v[204:205], v226 offset:36864
	v_mfma_f32_32x32x16_bf16 v[64:79], v[244:247], v[144:147], v[64:79]
	v_add_f32_e32 v154, v154, v180
	v_add_f32_e32 v170, v170, v198
	v_exp_f32_e32 v154, v154
	v_exp_f32_e32 v170, v170
	v_mfma_f32_32x32x16_bf16 v[80:95], v[244:247], v[160:163], v[80:95]
	v_add_f32_e32 v155, v155, v180
	v_add_f32_e32 v171, v171, v198
	v_exp_f32_e32 v155, v155
	v_exp_f32_e32 v171, v171
	ds_read_b64_tr_b16 v[244:245], v228 offset:36864
	ds_read_b64_tr_b16 v[246:247], v230 offset:36864
	v_mfma_f32_32x32x16_bf16 v[32:47], v[248:251], v[144:147], v[32:47]
	v_add_f32_e32 v156, v156, v180
	v_add_f32_e32 v172, v172, v198
	v_exp_f32_e32 v156, v156
	v_exp_f32_e32 v172, v172
	v_mfma_f32_32x32x16_bf16 v[48:63], v[248:251], v[160:163], v[48:63]
	v_add_f32_e32 v157, v157, v180
	v_add_f32_e32 v173, v173, v198
	v_exp_f32_e32 v157, v157
	v_exp_f32_e32 v173, v173
	v_mfma_f32_32x32x16_bf16 v[0:15], v[252:255], v[144:147], v[0:15]
	v_add_f32_e32 v158, v158, v180
	v_add_f32_e32 v174, v174, v198
	v_exp_f32_e32 v158, v158
	v_exp_f32_e32 v174, v174
	v_mfma_f32_32x32x16_bf16 v[16:31], v[252:255], v[160:163], v[16:31]
	v_add_f32_e32 v159, v159, v180
	v_add_f32_e32 v175, v175, v198
	v_exp_f32_e32 v159, v159
	v_exp_f32_e32 v175, v175
	v_cvt_pk_bf16_f32 v248, v152, v153
	v_cvt_pk_bf16_f32 v252, v168, v169
	v_cvt_pk_bf16_f32 v249, v154, v155
	v_cvt_pk_bf16_f32 v253, v170, v171
	v_cvt_pk_bf16_f32 v250, v156, v157
	v_cvt_pk_bf16_f32 v254, v172, v173
	v_cvt_pk_bf16_f32 v251, v158, v159
	v_cvt_pk_bf16_f32 v255, v174, v175
	s_nop 0
	s_waitcnt lgkmcnt(6)
	v_mfma_f32_32x32x16_bf16 v[112:127], v[148:151], v[248:251], v[112:127]
	v_add_f32_e32 v215, v215, v152
	v_add_f32_e32 v217, v217, v168
	v_mfma_f32_32x32x16_bf16 v[96:111], v[148:151], v[252:255], v[96:111]
	v_add_f32_e32 v215, v215, v153
	v_add_f32_e32 v217, v217, v169
	v_add_f32_e32 v215, v215, v154
	s_waitcnt lgkmcnt(4)
	v_mfma_f32_32x32x16_bf16 v[64:79], v[164:167], v[248:251], v[64:79]
	v_add_f32_e32 v217, v217, v170
	v_add_f32_e32 v215, v215, v155
	v_mfma_f32_32x32x16_bf16 v[80:95], v[164:167], v[252:255], v[80:95]
	v_add_f32_e32 v217, v217, v171
	v_add_f32_e32 v215, v215, v156
	v_add_f32_e32 v217, v217, v172
	s_waitcnt lgkmcnt(2)
	v_mfma_f32_32x32x16_bf16 v[32:47], v[202:205], v[248:251], v[32:47]
	v_add_f32_e32 v215, v215, v157
	v_add_f32_e32 v217, v217, v173
	v_mfma_f32_32x32x16_bf16 v[48:63], v[202:205], v[252:255], v[48:63]
	v_add_f32_e32 v215, v215, v158
	v_add_f32_e32 v217, v217, v174
	v_add_f32_e32 v215, v215, v159
	s_waitcnt lgkmcnt(0)
	v_mfma_f32_32x32x16_bf16 v[0:15], v[244:247], v[248:251], v[0:15]
	v_add_f32_e32 v217, v217, v175
	v_add_f32_e32 v197, v197, v215
	v_mfma_f32_32x32x16_bf16 v[16:31], v[244:247], v[252:255], v[16:31]
	v_add_f32_e32 v196, v196, v217
.Lat6_skip:
	s_branch .LBB0_753
.Lat1_diag:
	s_nop 2
	v_cndmask_b32_e64 v180, v160, v242, s[2:3]
	v_cndmask_b32_e64 v198, v144, v242, s[2:3]
	v_cndmask_b32_e64 v161, v242, v161, s[4:5]
	v_cndmask_b32_e64 v160, v180, v160, s[4:5]
	v_cndmask_b32_e64 v145, v242, v145, s[4:5]
	v_cndmask_b32_e64 v144, v198, v144, s[4:5]
	v_cndmask_b32_e64 v162, v162, v242, s[6:7]
	v_cndmask_b32_e64 v146, v146, v242, s[6:7]
	v_cndmask_b32_e64 v163, v163, v242, s[8:9]
	v_cndmask_b32_e64 v147, v147, v242, s[8:9]
	v_cndmask_b32_e64 v164, v164, v242, s[10:11]
	v_cndmask_b32_e64 v148, v148, v242, s[10:11]
	v_cndmask_b32_e64 v165, v165, v242, s[12:13]
	v_cndmask_b32_e64 v149, v149, v242, s[12:13]
	v_cndmask_b32_e64 v166, v166, v242, s[14:15]
	v_cndmask_b32_e64 v150, v150, v242, s[14:15]
	v_cndmask_b32_e64 v167, v167, v242, s[16:17]
	v_cndmask_b32_e64 v151, v151, v242, s[16:17]
	v_cndmask_b32_e64 v168, v168, v242, s[18:19]
	v_cndmask_b32_e64 v152, v152, v242, s[18:19]
	v_cndmask_b32_e64 v169, v169, v242, s[20:21]
	v_cndmask_b32_e64 v153, v153, v242, s[20:21]
	v_cndmask_b32_e64 v170, v170, v242, s[22:23]
	v_cndmask_b32_e64 v154, v154, v242, s[22:23]
	v_cndmask_b32_e64 v171, v171, v242, s[24:25]
	v_cndmask_b32_e64 v155, v155, v242, s[24:25]
	v_cndmask_b32_e64 v172, v172, v242, s[26:27]
	v_cndmask_b32_e64 v156, v156, v242, s[26:27]
	v_cndmask_b32_e64 v173, v173, v242, s[28:29]
	v_cndmask_b32_e64 v157, v157, v242, s[28:29]
	v_cndmask_b32_e64 v174, v174, v242, s[30:31]
	v_cndmask_b32_e64 v158, v158, v242, s[30:31]
	v_cndmask_b32_e64 v175, v175, v242, s[34:35]
	v_cndmask_b32_e64 v159, v159, v242, s[34:35]
